# residual epilogue loads device-scope (L1 bypass)
# speedup vs baseline: 1.0140x; 1.0006x over previous
;     ...
; #pragma unroll
;     for (int ai = 0; ai < 2; ++ai)
; #pragma unroll
;       for (int m = 0; m < 4; ++m)
;         epi(brow + ai * HALF + wr * 64 + m * 16 + fr, bcol + wc * 32, fq, acc[ai][0][m][0], acc[ai][0][m][1], acc[ai][1][m][0], acc[ai][1][m][1]);
.LBB0_1463:
	v_or_b32_e32 v0, s10, v218
	v_add_u32_e32 v136, v0, v215
	v_ashrrev_i32_e32 v137, 31, v136
	v_readlane_b32 s6, v253, 60
	v_lshl_or_b32 v0, v139, 5, s90
	v_lshlrev_b64 v[132:133], 12, v[136:137]
	v_readlane_b32 s7, v253, 61
	v_lshlrev_b64 v[134:135], 2, v[0:1]
	v_mov_b32_e32 v131, v1
	v_lshl_add_u64 v[132:133], s[6:7], 0, v[132:133]
	v_lshl_add_u64 v[132:133], v[132:133], 0, v[134:135]
	v_lshl_add_u64 v[132:133], v[132:133], 0, v[130:131]
	v_cndmask_b32_e64 v0, 0, 1, s[4:5]
	v_and_b32_e32 v134, 1, v210
	v_cmp_eq_u32_e32 vcc, 0, v134
	s_nop 1
	v_mov_b32_e32 v135, 0xfffff040
	v_cndmask_b32_e32 v134, v135, v1, vcc
	v_cndmask_b32_e32 v135, -1, v1, vcc
	v_lshl_add_u64 v[132:133], v[132:133], 0, v[134:135]
	s_mov_b64 s[6:7], 0x1000
	v_lshl_add_u64 v[136:137], v[132:133], 0, s[6:7]
	v_mov_b64_e32 v[138:139], v[132:133]
	v_mov_b64_e32 v[140:141], v[136:137]
	global_load_dwordx4 v[168:171], v[138:139], off sc1
	global_load_dwordx4 v[172:175], v[140:141], off sc1
	global_load_dwordx4 v[176:179], v[138:139], off offset:512 sc1
	global_load_dwordx4 v[180:183], v[140:141], off offset:512 sc1
	s_mov_b64 s[6:7], 0x10000
	v_lshl_add_u64 v[142:143], v[132:133], 0, s[6:7]
	v_lshl_add_u64 v[144:145], v[136:137], 0, s[6:7]
	global_load_dwordx4 v[184:187], v[142:143], off sc1
	global_load_dwordx4 v[188:191], v[144:145], off sc1
	global_load_dwordx4 v[192:195], v[142:143], off offset:512 sc1
	global_load_dwordx4 v[196:199], v[144:145], off offset:512 sc1
	s_mov_b64 s[6:7], 0x20000
	v_lshl_add_u64 v[146:147], v[132:133], 0, s[6:7]
	v_lshl_add_u64 v[148:149], v[136:137], 0, s[6:7]
	global_load_dwordx4 v[220:223], v[146:147], off sc1
	global_load_dwordx4 v[224:227], v[148:149], off sc1
	global_load_dwordx4 v[228:231], v[146:147], off offset:512 sc1
	global_load_dwordx4 v[232:235], v[148:149], off offset:512 sc1
	s_mov_b64 s[6:7], 0x30000
	v_lshl_add_u64 v[150:151], v[132:133], 0, s[6:7]
	v_lshl_add_u64 v[152:153], v[136:137], 0, s[6:7]
	global_load_dwordx4 v[236:239], v[150:151], off sc1
	global_load_dwordx4 v[240:243], v[152:153], off sc1
	global_load_dwordx4 v[244:247], v[150:151], off offset:512 sc1
	global_load_dwordx4 v[248:251], v[152:153], off offset:512 sc1
	v_mov_b32_dpp v200, v118 quad_perm:[1,0,3,2] row_mask:0xf bank_mask:0xf
	v_cndmask_b32_dpp v201, v114, v200, vcc quad_perm:[1,0,3,2] row_mask:0xf bank_mask:0xf
	v_cndmask_b32_e32 v118, v201, v118, vcc
	v_cndmask_b32_e32 v114, v114, v201, vcc
	v_mov_b32_dpp v200, v119 quad_perm:[1,0,3,2] row_mask:0xf bank_mask:0xf
	v_cndmask_b32_dpp v201, v115, v200, vcc quad_perm:[1,0,3,2] row_mask:0xf bank_mask:0xf
	v_cndmask_b32_e32 v119, v201, v119, vcc
	v_cndmask_b32_e32 v115, v115, v201, vcc
	v_mov_b32_dpp v200, v120 quad_perm:[1,0,3,2] row_mask:0xf bank_mask:0xf
	v_cndmask_b32_dpp v201, v116, v200, vcc quad_perm:[1,0,3,2] row_mask:0xf bank_mask:0xf
	v_cndmask_b32_e32 v120, v201, v120, vcc
	v_cndmask_b32_e32 v116, v116, v201, vcc
	v_mov_b32_dpp v200, v121 quad_perm:[1,0,3,2] row_mask:0xf bank_mask:0xf
	v_cndmask_b32_dpp v201, v117, v200, vcc quad_perm:[1,0,3,2] row_mask:0xf bank_mask:0xf
	v_cndmask_b32_e32 v121, v201, v121, vcc
	v_cndmask_b32_e32 v117, v117, v201, vcc
	v_mov_b32_dpp v200, v126 quad_perm:[1,0,3,2] row_mask:0xf bank_mask:0xf
	v_cndmask_b32_dpp v201, v122, v200, vcc quad_perm:[1,0,3,2] row_mask:0xf bank_mask:0xf
	v_cndmask_b32_e32 v126, v201, v126, vcc
	v_cndmask_b32_e32 v122, v122, v201, vcc
	v_mov_b32_dpp v200, v127 quad_perm:[1,0,3,2] row_mask:0xf bank_mask:0xf
	v_cndmask_b32_dpp v201, v123, v200, vcc quad_perm:[1,0,3,2] row_mask:0xf bank_mask:0xf
	v_cndmask_b32_e32 v127, v201, v127, vcc
	v_cndmask_b32_e32 v123, v123, v201, vcc
	v_mov_b32_dpp v200, v128 quad_perm:[1,0,3,2] row_mask:0xf bank_mask:0xf
	v_cndmask_b32_dpp v201, v124, v200, vcc quad_perm:[1,0,3,2] row_mask:0xf bank_mask:0xf
	v_cndmask_b32_e32 v128, v201, v128, vcc
	v_cndmask_b32_e32 v124, v124, v201, vcc
	v_mov_b32_dpp v200, v129 quad_perm:[1,0,3,2] row_mask:0xf bank_mask:0xf
	v_cndmask_b32_dpp v201, v125, v200, vcc quad_perm:[1,0,3,2] row_mask:0xf bank_mask:0xf
	v_cndmask_b32_e32 v129, v201, v129, vcc
	v_cndmask_b32_e32 v125, v125, v201, vcc
	s_waitcnt vmcnt(12)
	v_pk_add_f32 v[168:169], v[118:119], v[168:169]
	v_pk_add_f32 v[170:171], v[120:121], v[170:171]
	v_pk_add_f32 v[172:173], v[114:115], v[172:173]
	v_pk_add_f32 v[174:175], v[116:117], v[174:175]
	v_pk_add_f32 v[176:177], v[126:127], v[176:177]
	v_pk_add_f32 v[178:179], v[128:129], v[178:179]
	v_pk_add_f32 v[180:181], v[122:123], v[180:181]
	v_pk_add_f32 v[182:183], v[124:125], v[182:183]
	global_store_dwordx4 v[138:139], v[168:171], off sc1
	global_store_dwordx4 v[140:141], v[172:175], off sc1
	global_store_dwordx4 v[138:139], v[176:179], off offset:512 sc1
	global_store_dwordx4 v[140:141], v[180:183], off offset:512 sc1
	s_nop 1
	s_mov_b64 s[6:7], 0x80000
	v_lshl_add_u64 v[138:139], v[132:133], 0, s[6:7]
	v_lshl_add_u64 v[140:141], v[136:137], 0, s[6:7]
	global_load_dwordx4 v[168:171], v[138:139], off sc1
	global_load_dwordx4 v[172:175], v[140:141], off sc1
	global_load_dwordx4 v[176:179], v[138:139], off offset:512 sc1
	global_load_dwordx4 v[180:183], v[140:141], off offset:512 sc1
	v_mov_b32_dpp v200, v102 quad_perm:[1,0,3,2] row_mask:0xf bank_mask:0xf
	v_cndmask_b32_dpp v201, v98, v200, vcc quad_perm:[1,0,3,2] row_mask:0xf bank_mask:0xf
	v_cndmask_b32_e32 v102, v201, v102, vcc
	v_cndmask_b32_e32 v98, v98, v201, vcc
	v_mov_b32_dpp v200, v103 quad_perm:[1,0,3,2] row_mask:0xf bank_mask:0xf
	v_cndmask_b32_dpp v201, v99, v200, vcc quad_perm:[1,0,3,2] row_mask:0xf bank_mask:0xf
	v_cndmask_b32_e32 v103, v201, v103, vcc
	v_cndmask_b32_e32 v99, v99, v201, vcc
;     ...
; #pragma unroll
;     for (int ai = 0; ai < 2; ++ai)
; #pragma unroll
;       for (int m = 0; m < 4; ++m)
;         epi(brow + ai * HALF + wr * 64 + m * 16 + fr, bcol + wc * 32, fq, acc[ai][0][m][0], acc[ai][0][m][1], acc[ai][1][m][0], acc[ai][1][m][1]);
	v_mov_b32_dpp v200, v104 quad_perm:[1,0,3,2] row_mask:0xf bank_mask:0xf
	v_cndmask_b32_dpp v201, v100, v200, vcc quad_perm:[1,0,3,2] row_mask:0xf bank_mask:0xf
	v_cndmask_b32_e32 v104, v201, v104, vcc
	v_cndmask_b32_e32 v100, v100, v201, vcc
	v_mov_b32_dpp v200, v105 quad_perm:[1,0,3,2] row_mask:0xf bank_mask:0xf
	v_cndmask_b32_dpp v201, v101, v200, vcc quad_perm:[1,0,3,2] row_mask:0xf bank_mask:0xf
	v_cndmask_b32_e32 v105, v201, v105, vcc
	v_cndmask_b32_e32 v101, v101, v201, vcc
	v_mov_b32_dpp v200, v110 quad_perm:[1,0,3,2] row_mask:0xf bank_mask:0xf
	v_cndmask_b32_dpp v201, v106, v200, vcc quad_perm:[1,0,3,2] row_mask:0xf bank_mask:0xf
	v_cndmask_b32_e32 v110, v201, v110, vcc
	v_cndmask_b32_e32 v106, v106, v201, vcc
	v_mov_b32_dpp v200, v111 quad_perm:[1,0,3,2] row_mask:0xf bank_mask:0xf
	v_cndmask_b32_dpp v201, v107, v200, vcc quad_perm:[1,0,3,2] row_mask:0xf bank_mask:0xf
	v_cndmask_b32_e32 v111, v201, v111, vcc
	v_cndmask_b32_e32 v107, v107, v201, vcc
	v_mov_b32_dpp v200, v112 quad_perm:[1,0,3,2] row_mask:0xf bank_mask:0xf
	v_cndmask_b32_dpp v201, v108, v200, vcc quad_perm:[1,0,3,2] row_mask:0xf bank_mask:0xf
	v_cndmask_b32_e32 v112, v201, v112, vcc
	v_cndmask_b32_e32 v108, v108, v201, vcc
	v_mov_b32_dpp v200, v113 quad_perm:[1,0,3,2] row_mask:0xf bank_mask:0xf
	v_cndmask_b32_dpp v201, v109, v200, vcc quad_perm:[1,0,3,2] row_mask:0xf bank_mask:0xf
	v_cndmask_b32_e32 v113, v201, v113, vcc
	v_cndmask_b32_e32 v109, v109, v201, vcc
	s_waitcnt vmcnt(16)
	v_pk_add_f32 v[184:185], v[102:103], v[184:185]
	v_pk_add_f32 v[186:187], v[104:105], v[186:187]
	v_pk_add_f32 v[188:189], v[98:99], v[188:189]
	v_pk_add_f32 v[190:191], v[100:101], v[190:191]
	v_pk_add_f32 v[192:193], v[110:111], v[192:193]
	v_pk_add_f32 v[194:195], v[112:113], v[194:195]
	v_pk_add_f32 v[196:197], v[106:107], v[196:197]
	v_pk_add_f32 v[198:199], v[108:109], v[198:199]
	global_store_dwordx4 v[142:143], v[184:187], off sc1
	global_store_dwordx4 v[144:145], v[188:191], off sc1
	global_store_dwordx4 v[142:143], v[192:195], off offset:512 sc1
	global_store_dwordx4 v[144:145], v[196:199], off offset:512 sc1
	s_nop 1
	s_mov_b64 s[6:7], 0x90000
	v_lshl_add_u64 v[142:143], v[132:133], 0, s[6:7]
	v_lshl_add_u64 v[144:145], v[136:137], 0, s[6:7]
	global_load_dwordx4 v[184:187], v[142:143], off sc1
	global_load_dwordx4 v[188:191], v[144:145], off sc1
	global_load_dwordx4 v[192:195], v[142:143], off offset:512 sc1
	global_load_dwordx4 v[196:199], v[144:145], off offset:512 sc1
	v_mov_b32_dpp v200, v86 quad_perm:[1,0,3,2] row_mask:0xf bank_mask:0xf
	v_cndmask_b32_dpp v201, v82, v200, vcc quad_perm:[1,0,3,2] row_mask:0xf bank_mask:0xf
	v_cndmask_b32_e32 v86, v201, v86, vcc
	v_cndmask_b32_e32 v82, v82, v201, vcc
	v_mov_b32_dpp v200, v87 quad_perm:[1,0,3,2] row_mask:0xf bank_mask:0xf
	v_cndmask_b32_dpp v201, v83, v200, vcc quad_perm:[1,0,3,2] row_mask:0xf bank_mask:0xf
	v_cndmask_b32_e32 v87, v201, v87, vcc
	v_cndmask_b32_e32 v83, v83, v201, vcc
	v_mov_b32_dpp v200, v88 quad_perm:[1,0,3,2] row_mask:0xf bank_mask:0xf
	v_cndmask_b32_dpp v201, v84, v200, vcc quad_perm:[1,0,3,2] row_mask:0xf bank_mask:0xf
	v_cndmask_b32_e32 v88, v201, v88, vcc
	v_cndmask_b32_e32 v84, v84, v201, vcc
	v_mov_b32_dpp v200, v89 quad_perm:[1,0,3,2] row_mask:0xf bank_mask:0xf
	v_cndmask_b32_dpp v201, v85, v200, vcc quad_perm:[1,0,3,2] row_mask:0xf bank_mask:0xf
	v_cndmask_b32_e32 v89, v201, v89, vcc
	v_cndmask_b32_e32 v85, v85, v201, vcc
	v_mov_b32_dpp v200, v94 quad_perm:[1,0,3,2] row_mask:0xf bank_mask:0xf
	v_cndmask_b32_dpp v201, v90, v200, vcc quad_perm:[1,0,3,2] row_mask:0xf bank_mask:0xf
	v_cndmask_b32_e32 v94, v201, v94, vcc
	v_cndmask_b32_e32 v90, v90, v201, vcc
	v_mov_b32_dpp v200, v95 quad_perm:[1,0,3,2] row_mask:0xf bank_mask:0xf
	v_cndmask_b32_dpp v201, v91, v200, vcc quad_perm:[1,0,3,2] row_mask:0xf bank_mask:0xf
	v_cndmask_b32_e32 v95, v201, v95, vcc
	v_cndmask_b32_e32 v91, v91, v201, vcc
	v_mov_b32_dpp v200, v96 quad_perm:[1,0,3,2] row_mask:0xf bank_mask:0xf
	v_cndmask_b32_dpp v201, v92, v200, vcc quad_perm:[1,0,3,2] row_mask:0xf bank_mask:0xf
	v_cndmask_b32_e32 v96, v201, v96, vcc
	v_cndmask_b32_e32 v92, v92, v201, vcc
	v_mov_b32_dpp v200, v97 quad_perm:[1,0,3,2] row_mask:0xf bank_mask:0xf
	v_cndmask_b32_dpp v201, v93, v200, vcc quad_perm:[1,0,3,2] row_mask:0xf bank_mask:0xf
	v_cndmask_b32_e32 v97, v201, v97, vcc
	v_cndmask_b32_e32 v93, v93, v201, vcc
	s_waitcnt vmcnt(20)
;     ...
; #pragma unroll
;     for (int ai = 0; ai < 2; ++ai)
; #pragma unroll
;       for (int m = 0; m < 4; ++m)
;         epi(brow + ai * HALF + wr * 64 + m * 16 + fr, bcol + wc * 32, fq, acc[ai][0][m][0], acc[ai][0][m][1], acc[ai][1][m][0], acc[ai][1][m][1]);
	v_pk_add_f32 v[220:221], v[86:87], v[220:221]
	v_pk_add_f32 v[222:223], v[88:89], v[222:223]
	v_pk_add_f32 v[224:225], v[82:83], v[224:225]
	v_pk_add_f32 v[226:227], v[84:85], v[226:227]
	v_pk_add_f32 v[228:229], v[94:95], v[228:229]
	v_pk_add_f32 v[230:231], v[96:97], v[230:231]
	v_pk_add_f32 v[232:233], v[90:91], v[232:233]
	v_pk_add_f32 v[234:235], v[92:93], v[234:235]
	global_store_dwordx4 v[146:147], v[220:223], off sc1
	global_store_dwordx4 v[148:149], v[224:227], off sc1
	global_store_dwordx4 v[146:147], v[228:231], off offset:512 sc1
	global_store_dwordx4 v[148:149], v[232:235], off offset:512 sc1
	s_nop 1
	s_mov_b64 s[6:7], 0xa0000
	v_lshl_add_u64 v[146:147], v[132:133], 0, s[6:7]
	v_lshl_add_u64 v[148:149], v[136:137], 0, s[6:7]
	global_load_dwordx4 v[220:223], v[146:147], off sc1
	global_load_dwordx4 v[224:227], v[148:149], off sc1
	global_load_dwordx4 v[228:231], v[146:147], off offset:512 sc1
	global_load_dwordx4 v[232:235], v[148:149], off offset:512 sc1
	v_mov_b32_dpp v200, v70 quad_perm:[1,0,3,2] row_mask:0xf bank_mask:0xf
	v_cndmask_b32_dpp v201, v66, v200, vcc quad_perm:[1,0,3,2] row_mask:0xf bank_mask:0xf
	v_cndmask_b32_e32 v70, v201, v70, vcc
	v_cndmask_b32_e32 v66, v66, v201, vcc
	v_mov_b32_dpp v200, v71 quad_perm:[1,0,3,2] row_mask:0xf bank_mask:0xf
	v_cndmask_b32_dpp v201, v67, v200, vcc quad_perm:[1,0,3,2] row_mask:0xf bank_mask:0xf
	v_cndmask_b32_e32 v71, v201, v71, vcc
	v_cndmask_b32_e32 v67, v67, v201, vcc
	v_mov_b32_dpp v200, v72 quad_perm:[1,0,3,2] row_mask:0xf bank_mask:0xf
	v_cndmask_b32_dpp v201, v68, v200, vcc quad_perm:[1,0,3,2] row_mask:0xf bank_mask:0xf
	v_cndmask_b32_e32 v72, v201, v72, vcc
	v_cndmask_b32_e32 v68, v68, v201, vcc
	v_mov_b32_dpp v200, v73 quad_perm:[1,0,3,2] row_mask:0xf bank_mask:0xf
	v_cndmask_b32_dpp v201, v69, v200, vcc quad_perm:[1,0,3,2] row_mask:0xf bank_mask:0xf
	v_cndmask_b32_e32 v73, v201, v73, vcc
	v_cndmask_b32_e32 v69, v69, v201, vcc
	v_mov_b32_dpp v200, v78 quad_perm:[1,0,3,2] row_mask:0xf bank_mask:0xf
	v_cndmask_b32_dpp v201, v74, v200, vcc quad_perm:[1,0,3,2] row_mask:0xf bank_mask:0xf
	v_cndmask_b32_e32 v78, v201, v78, vcc
	v_cndmask_b32_e32 v74, v74, v201, vcc
	v_mov_b32_dpp v200, v79 quad_perm:[1,0,3,2] row_mask:0xf bank_mask:0xf
	v_cndmask_b32_dpp v201, v75, v200, vcc quad_perm:[1,0,3,2] row_mask:0xf bank_mask:0xf
	v_cndmask_b32_e32 v79, v201, v79, vcc
	v_cndmask_b32_e32 v75, v75, v201, vcc
	v_mov_b32_dpp v200, v80 quad_perm:[1,0,3,2] row_mask:0xf bank_mask:0xf
	v_cndmask_b32_dpp v201, v76, v200, vcc quad_perm:[1,0,3,2] row_mask:0xf bank_mask:0xf
	v_cndmask_b32_e32 v80, v201, v80, vcc
	v_cndmask_b32_e32 v76, v76, v201, vcc
	v_mov_b32_dpp v200, v81 quad_perm:[1,0,3,2] row_mask:0xf bank_mask:0xf
	v_cndmask_b32_dpp v201, v77, v200, vcc quad_perm:[1,0,3,2] row_mask:0xf bank_mask:0xf
	v_cndmask_b32_e32 v81, v201, v81, vcc
	v_cndmask_b32_e32 v77, v77, v201, vcc
	s_waitcnt vmcnt(24)
	v_pk_add_f32 v[236:237], v[70:71], v[236:237]
	v_pk_add_f32 v[238:239], v[72:73], v[238:239]
	v_pk_add_f32 v[240:241], v[66:67], v[240:241]
	v_pk_add_f32 v[242:243], v[68:69], v[242:243]
	v_pk_add_f32 v[244:245], v[78:79], v[244:245]
	v_pk_add_f32 v[246:247], v[80:81], v[246:247]
	v_pk_add_f32 v[248:249], v[74:75], v[248:249]
	v_pk_add_f32 v[250:251], v[76:77], v[250:251]
	global_store_dwordx4 v[150:151], v[236:239], off sc1
	global_store_dwordx4 v[152:153], v[240:243], off sc1
	global_store_dwordx4 v[150:151], v[244:247], off offset:512 sc1
	global_store_dwordx4 v[152:153], v[248:251], off offset:512 sc1
	s_nop 1
	s_mov_b64 s[6:7], 0xb0000
	v_lshl_add_u64 v[150:151], v[132:133], 0, s[6:7]
	v_lshl_add_u64 v[152:153], v[136:137], 0, s[6:7]
	global_load_dwordx4 v[236:239], v[150:151], off sc1
	global_load_dwordx4 v[240:243], v[152:153], off sc1
	global_load_dwordx4 v[244:247], v[150:151], off offset:512 sc1
	global_load_dwordx4 v[248:251], v[152:153], off offset:512 sc1
	v_mov_b32_dpp v200, v54 quad_perm:[1,0,3,2] row_mask:0xf bank_mask:0xf
	v_cndmask_b32_dpp v201, v50, v200, vcc quad_perm:[1,0,3,2] row_mask:0xf bank_mask:0xf
	v_cndmask_b32_e32 v54, v201, v54, vcc
	v_cndmask_b32_e32 v50, v50, v201, vcc
	v_mov_b32_dpp v200, v55 quad_perm:[1,0,3,2] row_mask:0xf bank_mask:0xf
	v_cndmask_b32_dpp v201, v51, v200, vcc quad_perm:[1,0,3,2] row_mask:0xf bank_mask:0xf
	v_cndmask_b32_e32 v55, v201, v55, vcc
	v_cndmask_b32_e32 v51, v51, v201, vcc
	v_mov_b32_dpp v200, v56 quad_perm:[1,0,3,2] row_mask:0xf bank_mask:0xf
	v_cndmask_b32_dpp v201, v52, v200, vcc quad_perm:[1,0,3,2] row_mask:0xf bank_mask:0xf
	v_cndmask_b32_e32 v56, v201, v56, vcc
	v_cndmask_b32_e32 v52, v52, v201, vcc
	v_mov_b32_dpp v200, v57 quad_perm:[1,0,3,2] row_mask:0xf bank_mask:0xf
	v_cndmask_b32_dpp v201, v53, v200, vcc quad_perm:[1,0,3,2] row_mask:0xf bank_mask:0xf
	v_cndmask_b32_e32 v57, v201, v57, vcc
	v_cndmask_b32_e32 v53, v53, v201, vcc
	v_mov_b32_dpp v200, v62 quad_perm:[1,0,3,2] row_mask:0xf bank_mask:0xf
	v_cndmask_b32_dpp v201, v58, v200, vcc quad_perm:[1,0,3,2] row_mask:0xf bank_mask:0xf
	v_cndmask_b32_e32 v62, v201, v62, vcc
	v_cndmask_b32_e32 v58, v58, v201, vcc
	v_mov_b32_dpp v200, v63 quad_perm:[1,0,3,2] row_mask:0xf bank_mask:0xf
	v_cndmask_b32_dpp v201, v59, v200, vcc quad_perm:[1,0,3,2] row_mask:0xf bank_mask:0xf
	v_cndmask_b32_e32 v63, v201, v63, vcc
	v_cndmask_b32_e32 v59, v59, v201, vcc
	v_mov_b32_dpp v200, v64 quad_perm:[1,0,3,2] row_mask:0xf bank_mask:0xf
	v_cndmask_b32_dpp v201, v60, v200, vcc quad_perm:[1,0,3,2] row_mask:0xf bank_mask:0xf
	v_cndmask_b32_e32 v64, v201, v64, vcc
	v_cndmask_b32_e32 v60, v60, v201, vcc
	v_mov_b32_dpp v200, v65 quad_perm:[1,0,3,2] row_mask:0xf bank_mask:0xf
	v_cndmask_b32_dpp v201, v61, v200, vcc quad_perm:[1,0,3,2] row_mask:0xf bank_mask:0xf
	v_cndmask_b32_e32 v65, v201, v65, vcc
	v_cndmask_b32_e32 v61, v61, v201, vcc
	s_waitcnt vmcnt(24)
;     ...
; #pragma unroll
;     for (int ai = 0; ai < 2; ++ai)
; #pragma unroll
;       for (int m = 0; m < 4; ++m)
;         epi(brow + ai * HALF + wr * 64 + m * 16 + fr, bcol + wc * 32, fq, acc[ai][0][m][0], acc[ai][0][m][1], acc[ai][1][m][0], acc[ai][1][m][1]);
	v_pk_add_f32 v[168:169], v[54:55], v[168:169]
	v_pk_add_f32 v[170:171], v[56:57], v[170:171]
	v_pk_add_f32 v[172:173], v[50:51], v[172:173]
	v_pk_add_f32 v[174:175], v[52:53], v[174:175]
	v_pk_add_f32 v[176:177], v[62:63], v[176:177]
	v_pk_add_f32 v[178:179], v[64:65], v[178:179]
	v_pk_add_f32 v[180:181], v[58:59], v[180:181]
	v_pk_add_f32 v[182:183], v[60:61], v[182:183]
	global_store_dwordx4 v[138:139], v[168:171], off sc1
	global_store_dwordx4 v[140:141], v[172:175], off sc1
	global_store_dwordx4 v[138:139], v[176:179], off offset:512 sc1
	global_store_dwordx4 v[140:141], v[180:183], off offset:512 sc1
	v_mov_b32_dpp v200, v38 quad_perm:[1,0,3,2] row_mask:0xf bank_mask:0xf
	v_cndmask_b32_dpp v201, v34, v200, vcc quad_perm:[1,0,3,2] row_mask:0xf bank_mask:0xf
	v_cndmask_b32_e32 v38, v201, v38, vcc
	v_cndmask_b32_e32 v34, v34, v201, vcc
	v_mov_b32_dpp v200, v39 quad_perm:[1,0,3,2] row_mask:0xf bank_mask:0xf
	v_cndmask_b32_dpp v201, v35, v200, vcc quad_perm:[1,0,3,2] row_mask:0xf bank_mask:0xf
	v_cndmask_b32_e32 v39, v201, v39, vcc
	v_cndmask_b32_e32 v35, v35, v201, vcc
	v_mov_b32_dpp v200, v40 quad_perm:[1,0,3,2] row_mask:0xf bank_mask:0xf
	v_cndmask_b32_dpp v201, v36, v200, vcc quad_perm:[1,0,3,2] row_mask:0xf bank_mask:0xf
	v_cndmask_b32_e32 v40, v201, v40, vcc
	v_cndmask_b32_e32 v36, v36, v201, vcc
	v_mov_b32_dpp v200, v41 quad_perm:[1,0,3,2] row_mask:0xf bank_mask:0xf
	v_cndmask_b32_dpp v201, v37, v200, vcc quad_perm:[1,0,3,2] row_mask:0xf bank_mask:0xf
	v_cndmask_b32_e32 v41, v201, v41, vcc
	v_cndmask_b32_e32 v37, v37, v201, vcc
	v_mov_b32_dpp v200, v46 quad_perm:[1,0,3,2] row_mask:0xf bank_mask:0xf
	v_cndmask_b32_dpp v201, v42, v200, vcc quad_perm:[1,0,3,2] row_mask:0xf bank_mask:0xf
	v_cndmask_b32_e32 v46, v201, v46, vcc
	v_cndmask_b32_e32 v42, v42, v201, vcc
	v_mov_b32_dpp v200, v47 quad_perm:[1,0,3,2] row_mask:0xf bank_mask:0xf
	v_cndmask_b32_dpp v201, v43, v200, vcc quad_perm:[1,0,3,2] row_mask:0xf bank_mask:0xf
	v_cndmask_b32_e32 v47, v201, v47, vcc
	v_cndmask_b32_e32 v43, v43, v201, vcc
	v_mov_b32_dpp v200, v48 quad_perm:[1,0,3,2] row_mask:0xf bank_mask:0xf
	v_cndmask_b32_dpp v201, v44, v200, vcc quad_perm:[1,0,3,2] row_mask:0xf bank_mask:0xf
	v_cndmask_b32_e32 v48, v201, v48, vcc
	v_cndmask_b32_e32 v44, v44, v201, vcc
	v_mov_b32_dpp v200, v49 quad_perm:[1,0,3,2] row_mask:0xf bank_mask:0xf
	v_cndmask_b32_dpp v201, v45, v200, vcc quad_perm:[1,0,3,2] row_mask:0xf bank_mask:0xf
	v_cndmask_b32_e32 v49, v201, v49, vcc
	v_cndmask_b32_e32 v45, v45, v201, vcc
	s_waitcnt vmcnt(20)
	v_pk_add_f32 v[184:185], v[38:39], v[184:185]
	v_pk_add_f32 v[186:187], v[40:41], v[186:187]
	v_pk_add_f32 v[188:189], v[34:35], v[188:189]
	v_pk_add_f32 v[190:191], v[36:37], v[190:191]
	v_pk_add_f32 v[192:193], v[46:47], v[192:193]
	v_pk_add_f32 v[194:195], v[48:49], v[194:195]
	v_pk_add_f32 v[196:197], v[42:43], v[196:197]
	v_pk_add_f32 v[198:199], v[44:45], v[198:199]
	global_store_dwordx4 v[142:143], v[184:187], off sc1
	global_store_dwordx4 v[144:145], v[188:191], off sc1
	global_store_dwordx4 v[142:143], v[192:195], off offset:512 sc1
	global_store_dwordx4 v[144:145], v[196:199], off offset:512 sc1
	v_mov_b32_dpp v200, v22 quad_perm:[1,0,3,2] row_mask:0xf bank_mask:0xf
	v_cndmask_b32_dpp v201, v18, v200, vcc quad_perm:[1,0,3,2] row_mask:0xf bank_mask:0xf
	v_cndmask_b32_e32 v22, v201, v22, vcc
	v_cndmask_b32_e32 v18, v18, v201, vcc
	v_mov_b32_dpp v200, v23 quad_perm:[1,0,3,2] row_mask:0xf bank_mask:0xf
	v_cndmask_b32_dpp v201, v19, v200, vcc quad_perm:[1,0,3,2] row_mask:0xf bank_mask:0xf
	v_cndmask_b32_e32 v23, v201, v23, vcc
	v_cndmask_b32_e32 v19, v19, v201, vcc
	v_mov_b32_dpp v200, v24 quad_perm:[1,0,3,2] row_mask:0xf bank_mask:0xf
	v_cndmask_b32_dpp v201, v20, v200, vcc quad_perm:[1,0,3,2] row_mask:0xf bank_mask:0xf
	v_cndmask_b32_e32 v24, v201, v24, vcc
	v_cndmask_b32_e32 v20, v20, v201, vcc
	v_mov_b32_dpp v200, v25 quad_perm:[1,0,3,2] row_mask:0xf bank_mask:0xf
	v_cndmask_b32_dpp v201, v21, v200, vcc quad_perm:[1,0,3,2] row_mask:0xf bank_mask:0xf
	v_cndmask_b32_e32 v25, v201, v25, vcc
	v_cndmask_b32_e32 v21, v21, v201, vcc
	v_mov_b32_dpp v200, v30 quad_perm:[1,0,3,2] row_mask:0xf bank_mask:0xf
	v_cndmask_b32_dpp v201, v26, v200, vcc quad_perm:[1,0,3,2] row_mask:0xf bank_mask:0xf
	v_cndmask_b32_e32 v30, v201, v30, vcc
	v_cndmask_b32_e32 v26, v26, v201, vcc
	v_mov_b32_dpp v200, v31 quad_perm:[1,0,3,2] row_mask:0xf bank_mask:0xf
	v_cndmask_b32_dpp v201, v27, v200, vcc quad_perm:[1,0,3,2] row_mask:0xf bank_mask:0xf
	v_cndmask_b32_e32 v31, v201, v31, vcc
	v_cndmask_b32_e32 v27, v27, v201, vcc
	v_mov_b32_dpp v200, v32 quad_perm:[1,0,3,2] row_mask:0xf bank_mask:0xf
	v_cndmask_b32_dpp v201, v28, v200, vcc quad_perm:[1,0,3,2] row_mask:0xf bank_mask:0xf
	v_cndmask_b32_e32 v32, v201, v32, vcc
	v_cndmask_b32_e32 v28, v28, v201, vcc
	v_mov_b32_dpp v200, v33 quad_perm:[1,0,3,2] row_mask:0xf bank_mask:0xf
	v_cndmask_b32_dpp v201, v29, v200, vcc quad_perm:[1,0,3,2] row_mask:0xf bank_mask:0xf
	v_cndmask_b32_e32 v33, v201, v33, vcc
	v_cndmask_b32_e32 v29, v29, v201, vcc
	s_waitcnt vmcnt(16)
; #define WAIT_V(n) asm volatile("s_waitcnt vmcnt(" #n ")" ::: "memory")
;     ...
;   if (!have_next) { WAIT_V(0); __syncthreads(); }
	v_pk_add_f32 v[220:221], v[22:23], v[220:221]
	v_pk_add_f32 v[222:223], v[24:25], v[222:223]
	v_pk_add_f32 v[224:225], v[18:19], v[224:225]
	v_pk_add_f32 v[226:227], v[20:21], v[226:227]
	v_pk_add_f32 v[228:229], v[30:31], v[228:229]
	v_pk_add_f32 v[230:231], v[32:33], v[230:231]
	v_pk_add_f32 v[232:233], v[26:27], v[232:233]
	v_pk_add_f32 v[234:235], v[28:29], v[234:235]
	global_store_dwordx4 v[146:147], v[220:223], off sc1
	global_store_dwordx4 v[148:149], v[224:227], off sc1
	global_store_dwordx4 v[146:147], v[228:231], off offset:512 sc1
	global_store_dwordx4 v[148:149], v[232:235], off offset:512 sc1
	v_mov_b32_dpp v200, v14 quad_perm:[1,0,3,2] row_mask:0xf bank_mask:0xf
	v_cndmask_b32_dpp v201, v6, v200, vcc quad_perm:[1,0,3,2] row_mask:0xf bank_mask:0xf
	v_cndmask_b32_e32 v14, v201, v14, vcc
	v_cndmask_b32_e32 v6, v6, v201, vcc
	v_mov_b32_dpp v200, v15 quad_perm:[1,0,3,2] row_mask:0xf bank_mask:0xf
	v_cndmask_b32_dpp v201, v7, v200, vcc quad_perm:[1,0,3,2] row_mask:0xf bank_mask:0xf
	v_cndmask_b32_e32 v15, v201, v15, vcc
	v_cndmask_b32_e32 v7, v7, v201, vcc
	v_mov_b32_dpp v200, v16 quad_perm:[1,0,3,2] row_mask:0xf bank_mask:0xf
	v_cndmask_b32_dpp v201, v8, v200, vcc quad_perm:[1,0,3,2] row_mask:0xf bank_mask:0xf
	v_cndmask_b32_e32 v16, v201, v16, vcc
	v_cndmask_b32_e32 v8, v8, v201, vcc
	v_mov_b32_dpp v200, v17 quad_perm:[1,0,3,2] row_mask:0xf bank_mask:0xf
	v_cndmask_b32_dpp v201, v9, v200, vcc quad_perm:[1,0,3,2] row_mask:0xf bank_mask:0xf
	v_cndmask_b32_e32 v17, v201, v17, vcc
	v_cndmask_b32_e32 v9, v9, v201, vcc
	v_mov_b32_dpp v200, v10 quad_perm:[1,0,3,2] row_mask:0xf bank_mask:0xf
	v_cndmask_b32_dpp v201, v2, v200, vcc quad_perm:[1,0,3,2] row_mask:0xf bank_mask:0xf
	v_cndmask_b32_e32 v10, v201, v10, vcc
	v_cndmask_b32_e32 v2, v2, v201, vcc
	v_mov_b32_dpp v200, v11 quad_perm:[1,0,3,2] row_mask:0xf bank_mask:0xf
	v_cndmask_b32_dpp v201, v3, v200, vcc quad_perm:[1,0,3,2] row_mask:0xf bank_mask:0xf
	v_cndmask_b32_e32 v11, v201, v11, vcc
	v_cndmask_b32_e32 v3, v3, v201, vcc
	v_mov_b32_dpp v200, v12 quad_perm:[1,0,3,2] row_mask:0xf bank_mask:0xf
	v_cndmask_b32_dpp v201, v4, v200, vcc quad_perm:[1,0,3,2] row_mask:0xf bank_mask:0xf
	v_cndmask_b32_e32 v12, v201, v12, vcc
	v_cndmask_b32_e32 v4, v4, v201, vcc
	v_mov_b32_dpp v200, v13 quad_perm:[1,0,3,2] row_mask:0xf bank_mask:0xf
	v_cndmask_b32_dpp v201, v5, v200, vcc quad_perm:[1,0,3,2] row_mask:0xf bank_mask:0xf
	v_cndmask_b32_e32 v13, v201, v13, vcc
	v_cndmask_b32_e32 v5, v5, v201, vcc
	s_waitcnt vmcnt(12)
	v_pk_add_f32 v[236:237], v[14:15], v[236:237]
	v_pk_add_f32 v[238:239], v[16:17], v[238:239]
	v_pk_add_f32 v[240:241], v[6:7], v[240:241]
	v_pk_add_f32 v[242:243], v[8:9], v[242:243]
	v_pk_add_f32 v[244:245], v[10:11], v[244:245]
	v_pk_add_f32 v[246:247], v[12:13], v[246:247]
	v_pk_add_f32 v[248:249], v[2:3], v[248:249]
	v_pk_add_f32 v[250:251], v[4:5], v[250:251]
	global_store_dwordx4 v[150:151], v[236:239], off sc1
	global_store_dwordx4 v[152:153], v[240:243], off sc1
	global_store_dwordx4 v[150:151], v[244:247], off offset:512 sc1
	global_store_dwordx4 v[152:153], v[248:251], off offset:512 sc1
	v_cmp_ne_u32_e64 s[6:7], 1, v0
	s_andn2_b64 vcc, exec, s[4:5]
	s_cbranch_vccnz .LBB0_1450
	s_waitcnt vmcnt(0)
	s_waitcnt lgkmcnt(0)
	s_barrier
	s_branch .LBB0_1450

;     ...
; #pragma unroll
;     for (int ai = 0; ai < 2; ++ai)
; #pragma unroll
;       for (int m = 0; m < 4; ++m)
;         epi(brow + ai * HALF + wr * 64 + m * 16 + fr, bcol + wc * 32, fq, acc[ai][0][m][0], acc[ai][0][m][1], acc[ai][1][m][0], acc[ai][1][m][1]);
.LBB0_1487:
	v_or_b32_e32 v0, s8, v140
	v_readlane_b32 s16, v253, 24
	v_add_u32_e32 v136, v0, v141
	v_readlane_b32 s17, v253, 25
	v_ashrrev_i32_e32 v137, 31, v136
	v_readlane_b32 s18, v253, 26
	v_readlane_b32 s19, v253, 27
	v_readlane_b32 s20, v253, 28
	v_readlane_b32 s21, v253, 29
	s_mov_b64 s[8:9], s[16:17]
	v_lshl_or_b32 v0, v139, 5, s90
	s_mov_b32 s6, 0x8000
	v_lshlrev_b64 v[138:139], 12, v[136:137]
	s_mov_b64 s[10:11], s[18:19]
	v_lshlrev_b32_e32 v20, 12, v140
	v_mov_b32_e32 v21, v1
	v_cmp_gt_i32_e32 vcc, s6, v136
	v_lshl_add_u64 v[18:19], s[8:9], 0, v[138:139]
	v_lshl_add_u64 v[134:135], s[10:11], 0, v[20:21]
	v_readlane_b32 s10, v253, 60
	v_cndmask_b32_e32 v19, v135, v19, vcc
	v_cndmask_b32_e32 v18, v134, v18, vcc
	v_readlane_b32 s11, v253, 61
	v_lshlrev_b64 v[132:133], 2, v[0:1]
	v_mov_b32_e32 v131, v1
	v_lshl_add_u64 v[20:21], s[10:11], 0, v[138:139]
	v_lshl_add_u64 v[18:19], v[18:19], 0, v[132:133]
	v_lshl_add_u64 v[20:21], v[20:21], 0, v[132:133]
	v_lshl_add_u64 v[148:149], v[18:19], 0, v[130:131]
	v_lshl_add_u64 v[152:153], v[20:21], 0, v[130:131]
	v_readlane_b32 s22, v253, 30
	v_readlane_b32 s23, v253, 31
	v_readlane_b32 s24, v253, 32
	v_readlane_b32 s25, v253, 33
	v_readlane_b32 s26, v253, 34
	v_readlane_b32 s27, v253, 35
	v_readlane_b32 s28, v253, 36
	v_readlane_b32 s29, v253, 37
	v_readlane_b32 s30, v253, 38
	v_readlane_b32 s31, v253, 39
	s_mov_b64 s[12:13], s[20:21]
	v_sub_co_u32_e32 v134, vcc, v152, v148
	v_subb_co_u32_e32 v135, vcc, v153, v149, vcc
	s_nop 0
	v_readfirstlane_b32 s98, v134
	v_readfirstlane_b32 s99, v135
	v_and_b32_e32 v134, 1, v210
	v_cmp_eq_u32_e32 vcc, 0, v134
	s_nop 1
	v_mov_b32_e32 v135, 0xfffff040
	v_cndmask_b32_e32 v134, v135, v1, vcc
	v_cndmask_b32_e32 v135, -1, v1, vcc
	v_lshl_add_u64 v[132:133], v[148:149], 0, v[134:135]
	s_mov_b64 s[96:97], 0x1000
	v_lshl_add_u64 v[136:137], v[132:133], 0, s[96:97]
	v_mov_b64_e32 v[138:139], v[132:133]
	v_mov_b64_e32 v[140:141], v[136:137]
	global_load_dwordx4 v[168:171], v[138:139], off sc1
	global_load_dwordx4 v[172:175], v[140:141], off sc1
	global_load_dwordx4 v[176:179], v[138:139], off offset:512 sc1
	global_load_dwordx4 v[180:183], v[140:141], off offset:512 sc1
	s_mov_b64 s[96:97], 0x10000
	v_lshl_add_u64 v[142:143], v[132:133], 0, s[96:97]
	v_lshl_add_u64 v[144:145], v[136:137], 0, s[96:97]
	global_load_dwordx4 v[184:187], v[142:143], off sc1
	global_load_dwordx4 v[188:191], v[144:145], off sc1
	global_load_dwordx4 v[192:195], v[142:143], off offset:512 sc1
	global_load_dwordx4 v[196:199], v[144:145], off offset:512 sc1
	s_mov_b64 s[96:97], 0x20000
	v_lshl_add_u64 v[146:147], v[132:133], 0, s[96:97]
	v_lshl_add_u64 v[148:149], v[136:137], 0, s[96:97]
	global_load_dwordx4 v[224:227], v[146:147], off sc1
	global_load_dwordx4 v[228:231], v[148:149], off sc1
	global_load_dwordx4 v[232:235], v[146:147], off offset:512 sc1
	global_load_dwordx4 v[236:239], v[148:149], off offset:512 sc1
	s_mov_b64 s[96:97], 0x30000
	v_lshl_add_u64 v[150:151], v[132:133], 0, s[96:97]
	v_lshl_add_u64 v[152:153], v[136:137], 0, s[96:97]
	global_load_dwordx4 v[240:243], v[150:151], off sc1
	global_load_dwordx4 v[244:247], v[152:153], off sc1
	global_load_dwordx4 v[248:251], v[150:151], off offset:512 sc1
	global_load_dwordx4 v[206:209], v[152:153], off offset:512 sc1
	v_mov_b32_dpp v200, v118 quad_perm:[1,0,3,2] row_mask:0xf bank_mask:0xf
	v_cndmask_b32_dpp v201, v114, v200, vcc quad_perm:[1,0,3,2] row_mask:0xf bank_mask:0xf
	v_cndmask_b32_e32 v118, v201, v118, vcc
	v_cndmask_b32_e32 v114, v114, v201, vcc
	v_mov_b32_dpp v200, v119 quad_perm:[1,0,3,2] row_mask:0xf bank_mask:0xf
	v_cndmask_b32_dpp v201, v115, v200, vcc quad_perm:[1,0,3,2] row_mask:0xf bank_mask:0xf
	v_cndmask_b32_e32 v119, v201, v119, vcc
	v_cndmask_b32_e32 v115, v115, v201, vcc
	v_mov_b32_dpp v200, v120 quad_perm:[1,0,3,2] row_mask:0xf bank_mask:0xf
	v_cndmask_b32_dpp v201, v116, v200, vcc quad_perm:[1,0,3,2] row_mask:0xf bank_mask:0xf
	v_cndmask_b32_e32 v120, v201, v120, vcc
	v_cndmask_b32_e32 v116, v116, v201, vcc
	v_mov_b32_dpp v200, v121 quad_perm:[1,0,3,2] row_mask:0xf bank_mask:0xf
	v_cndmask_b32_dpp v201, v117, v200, vcc quad_perm:[1,0,3,2] row_mask:0xf bank_mask:0xf
	v_cndmask_b32_e32 v121, v201, v121, vcc
	v_cndmask_b32_e32 v117, v117, v201, vcc
	v_mov_b32_dpp v200, v126 quad_perm:[1,0,3,2] row_mask:0xf bank_mask:0xf
	v_cndmask_b32_dpp v201, v122, v200, vcc quad_perm:[1,0,3,2] row_mask:0xf bank_mask:0xf
	v_cndmask_b32_e32 v126, v201, v126, vcc
	v_cndmask_b32_e32 v122, v122, v201, vcc
	v_mov_b32_dpp v200, v127 quad_perm:[1,0,3,2] row_mask:0xf bank_mask:0xf
	v_cndmask_b32_dpp v201, v123, v200, vcc quad_perm:[1,0,3,2] row_mask:0xf bank_mask:0xf
	v_cndmask_b32_e32 v127, v201, v127, vcc
	v_cndmask_b32_e32 v123, v123, v201, vcc
	v_mov_b32_dpp v200, v128 quad_perm:[1,0,3,2] row_mask:0xf bank_mask:0xf
	v_cndmask_b32_dpp v201, v124, v200, vcc quad_perm:[1,0,3,2] row_mask:0xf bank_mask:0xf
	v_cndmask_b32_e32 v128, v201, v128, vcc
	v_cndmask_b32_e32 v124, v124, v201, vcc
	v_mov_b32_dpp v200, v129 quad_perm:[1,0,3,2] row_mask:0xf bank_mask:0xf
	v_cndmask_b32_dpp v201, v125, v200, vcc quad_perm:[1,0,3,2] row_mask:0xf bank_mask:0xf
	v_cndmask_b32_e32 v129, v201, v129, vcc
	v_cndmask_b32_e32 v125, v125, v201, vcc
	s_waitcnt vmcnt(12)
;     ...
; #pragma unroll
;     for (int ai = 0; ai < 2; ++ai)
; #pragma unroll
;       for (int m = 0; m < 4; ++m)
;         epi(brow + ai * HALF + wr * 64 + m * 16 + fr, bcol + wc * 32, fq, acc[ai][0][m][0], acc[ai][0][m][1], acc[ai][1][m][0], acc[ai][1][m][1]);
	v_pk_add_f32 v[168:169], v[118:119], v[168:169]
	v_pk_add_f32 v[170:171], v[120:121], v[170:171]
	v_pk_add_f32 v[172:173], v[114:115], v[172:173]
	v_pk_add_f32 v[174:175], v[116:117], v[174:175]
	v_pk_add_f32 v[176:177], v[126:127], v[176:177]
	v_pk_add_f32 v[178:179], v[128:129], v[178:179]
	v_pk_add_f32 v[180:181], v[122:123], v[180:181]
	v_pk_add_f32 v[182:183], v[124:125], v[182:183]
	v_lshl_add_u64 v[202:203], v[138:139], 0, s[98:99]
	v_lshl_add_u64 v[204:205], v[140:141], 0, s[98:99]
	global_store_dwordx4 v[202:203], v[168:171], off sc1
	global_store_dwordx4 v[204:205], v[172:175], off sc1
	global_store_dwordx4 v[202:203], v[176:179], off offset:512 sc1
	global_store_dwordx4 v[204:205], v[180:183], off offset:512 sc1
	s_nop 1
	s_mov_b64 s[96:97], 0x80000
	v_lshl_add_u64 v[138:139], v[132:133], 0, s[96:97]
	v_lshl_add_u64 v[140:141], v[136:137], 0, s[96:97]
	global_load_dwordx4 v[168:171], v[138:139], off sc1
	global_load_dwordx4 v[172:175], v[140:141], off sc1
	global_load_dwordx4 v[176:179], v[138:139], off offset:512 sc1
	global_load_dwordx4 v[180:183], v[140:141], off offset:512 sc1
	v_mov_b32_dpp v200, v102 quad_perm:[1,0,3,2] row_mask:0xf bank_mask:0xf
	v_cndmask_b32_dpp v201, v98, v200, vcc quad_perm:[1,0,3,2] row_mask:0xf bank_mask:0xf
	v_cndmask_b32_e32 v102, v201, v102, vcc
	v_cndmask_b32_e32 v98, v98, v201, vcc
	v_mov_b32_dpp v200, v103 quad_perm:[1,0,3,2] row_mask:0xf bank_mask:0xf
	v_cndmask_b32_dpp v201, v99, v200, vcc quad_perm:[1,0,3,2] row_mask:0xf bank_mask:0xf
	v_cndmask_b32_e32 v103, v201, v103, vcc
	v_cndmask_b32_e32 v99, v99, v201, vcc
	v_mov_b32_dpp v200, v104 quad_perm:[1,0,3,2] row_mask:0xf bank_mask:0xf
	v_cndmask_b32_dpp v201, v100, v200, vcc quad_perm:[1,0,3,2] row_mask:0xf bank_mask:0xf
	v_cndmask_b32_e32 v104, v201, v104, vcc
	v_cndmask_b32_e32 v100, v100, v201, vcc
	v_mov_b32_dpp v200, v105 quad_perm:[1,0,3,2] row_mask:0xf bank_mask:0xf
	v_cndmask_b32_dpp v201, v101, v200, vcc quad_perm:[1,0,3,2] row_mask:0xf bank_mask:0xf
	v_cndmask_b32_e32 v105, v201, v105, vcc
	v_cndmask_b32_e32 v101, v101, v201, vcc
	v_mov_b32_dpp v200, v110 quad_perm:[1,0,3,2] row_mask:0xf bank_mask:0xf
	v_cndmask_b32_dpp v201, v106, v200, vcc quad_perm:[1,0,3,2] row_mask:0xf bank_mask:0xf
	v_cndmask_b32_e32 v110, v201, v110, vcc
	v_cndmask_b32_e32 v106, v106, v201, vcc
	v_mov_b32_dpp v200, v111 quad_perm:[1,0,3,2] row_mask:0xf bank_mask:0xf
	v_cndmask_b32_dpp v201, v107, v200, vcc quad_perm:[1,0,3,2] row_mask:0xf bank_mask:0xf
	v_cndmask_b32_e32 v111, v201, v111, vcc
	v_cndmask_b32_e32 v107, v107, v201, vcc
	v_mov_b32_dpp v200, v112 quad_perm:[1,0,3,2] row_mask:0xf bank_mask:0xf
	v_cndmask_b32_dpp v201, v108, v200, vcc quad_perm:[1,0,3,2] row_mask:0xf bank_mask:0xf
	v_cndmask_b32_e32 v112, v201, v112, vcc
	v_cndmask_b32_e32 v108, v108, v201, vcc
	v_mov_b32_dpp v200, v113 quad_perm:[1,0,3,2] row_mask:0xf bank_mask:0xf
	v_cndmask_b32_dpp v201, v109, v200, vcc quad_perm:[1,0,3,2] row_mask:0xf bank_mask:0xf
	v_cndmask_b32_e32 v113, v201, v113, vcc
	v_cndmask_b32_e32 v109, v109, v201, vcc
	s_waitcnt vmcnt(16)
	v_pk_add_f32 v[184:185], v[102:103], v[184:185]
	v_pk_add_f32 v[186:187], v[104:105], v[186:187]
	v_pk_add_f32 v[188:189], v[98:99], v[188:189]
	v_pk_add_f32 v[190:191], v[100:101], v[190:191]
	v_pk_add_f32 v[192:193], v[110:111], v[192:193]
	v_pk_add_f32 v[194:195], v[112:113], v[194:195]
	v_pk_add_f32 v[196:197], v[106:107], v[196:197]
	v_pk_add_f32 v[198:199], v[108:109], v[198:199]
	v_lshl_add_u64 v[202:203], v[142:143], 0, s[98:99]
	v_lshl_add_u64 v[204:205], v[144:145], 0, s[98:99]
	global_store_dwordx4 v[202:203], v[184:187], off sc1
	global_store_dwordx4 v[204:205], v[188:191], off sc1
	global_store_dwordx4 v[202:203], v[192:195], off offset:512 sc1
	global_store_dwordx4 v[204:205], v[196:199], off offset:512 sc1
	s_nop 1
	s_mov_b64 s[96:97], 0x90000
	v_lshl_add_u64 v[142:143], v[132:133], 0, s[96:97]
	v_lshl_add_u64 v[144:145], v[136:137], 0, s[96:97]
	global_load_dwordx4 v[184:187], v[142:143], off sc1
	global_load_dwordx4 v[188:191], v[144:145], off sc1
	global_load_dwordx4 v[192:195], v[142:143], off offset:512 sc1
	global_load_dwordx4 v[196:199], v[144:145], off offset:512 sc1
	v_mov_b32_dpp v200, v86 quad_perm:[1,0,3,2] row_mask:0xf bank_mask:0xf
	v_cndmask_b32_dpp v201, v82, v200, vcc quad_perm:[1,0,3,2] row_mask:0xf bank_mask:0xf
	v_cndmask_b32_e32 v86, v201, v86, vcc
	v_cndmask_b32_e32 v82, v82, v201, vcc
	v_mov_b32_dpp v200, v87 quad_perm:[1,0,3,2] row_mask:0xf bank_mask:0xf
	v_cndmask_b32_dpp v201, v83, v200, vcc quad_perm:[1,0,3,2] row_mask:0xf bank_mask:0xf
	v_cndmask_b32_e32 v87, v201, v87, vcc
	v_cndmask_b32_e32 v83, v83, v201, vcc
	v_mov_b32_dpp v200, v88 quad_perm:[1,0,3,2] row_mask:0xf bank_mask:0xf
	v_cndmask_b32_dpp v201, v84, v200, vcc quad_perm:[1,0,3,2] row_mask:0xf bank_mask:0xf
	v_cndmask_b32_e32 v88, v201, v88, vcc
	v_cndmask_b32_e32 v84, v84, v201, vcc
	v_mov_b32_dpp v200, v89 quad_perm:[1,0,3,2] row_mask:0xf bank_mask:0xf
	v_cndmask_b32_dpp v201, v85, v200, vcc quad_perm:[1,0,3,2] row_mask:0xf bank_mask:0xf
	v_cndmask_b32_e32 v89, v201, v89, vcc
	v_cndmask_b32_e32 v85, v85, v201, vcc
	v_mov_b32_dpp v200, v94 quad_perm:[1,0,3,2] row_mask:0xf bank_mask:0xf
	v_cndmask_b32_dpp v201, v90, v200, vcc quad_perm:[1,0,3,2] row_mask:0xf bank_mask:0xf
	v_cndmask_b32_e32 v94, v201, v94, vcc
	v_cndmask_b32_e32 v90, v90, v201, vcc
	v_mov_b32_dpp v200, v95 quad_perm:[1,0,3,2] row_mask:0xf bank_mask:0xf
	v_cndmask_b32_dpp v201, v91, v200, vcc quad_perm:[1,0,3,2] row_mask:0xf bank_mask:0xf
	v_cndmask_b32_e32 v95, v201, v95, vcc
	v_cndmask_b32_e32 v91, v91, v201, vcc
	v_mov_b32_dpp v200, v96 quad_perm:[1,0,3,2] row_mask:0xf bank_mask:0xf
	v_cndmask_b32_dpp v201, v92, v200, vcc quad_perm:[1,0,3,2] row_mask:0xf bank_mask:0xf
	v_cndmask_b32_e32 v96, v201, v96, vcc
	v_cndmask_b32_e32 v92, v92, v201, vcc
	v_mov_b32_dpp v200, v97 quad_perm:[1,0,3,2] row_mask:0xf bank_mask:0xf
	v_cndmask_b32_dpp v201, v93, v200, vcc quad_perm:[1,0,3,2] row_mask:0xf bank_mask:0xf
	v_cndmask_b32_e32 v97, v201, v97, vcc
	v_cndmask_b32_e32 v93, v93, v201, vcc
	s_waitcnt vmcnt(20)
;     ...
; #pragma unroll
;     for (int ai = 0; ai < 2; ++ai)
; #pragma unroll
;       for (int m = 0; m < 4; ++m)
;         epi(brow + ai * HALF + wr * 64 + m * 16 + fr, bcol + wc * 32, fq, acc[ai][0][m][0], acc[ai][0][m][1], acc[ai][1][m][0], acc[ai][1][m][1]);
	v_pk_add_f32 v[224:225], v[86:87], v[224:225]
	v_pk_add_f32 v[226:227], v[88:89], v[226:227]
	v_pk_add_f32 v[228:229], v[82:83], v[228:229]
	v_pk_add_f32 v[230:231], v[84:85], v[230:231]
	v_pk_add_f32 v[232:233], v[94:95], v[232:233]
	v_pk_add_f32 v[234:235], v[96:97], v[234:235]
	v_pk_add_f32 v[236:237], v[90:91], v[236:237]
	v_pk_add_f32 v[238:239], v[92:93], v[238:239]
	v_lshl_add_u64 v[202:203], v[146:147], 0, s[98:99]
	v_lshl_add_u64 v[204:205], v[148:149], 0, s[98:99]
	global_store_dwordx4 v[202:203], v[224:227], off sc1
	global_store_dwordx4 v[204:205], v[228:231], off sc1
	global_store_dwordx4 v[202:203], v[232:235], off offset:512 sc1
	global_store_dwordx4 v[204:205], v[236:239], off offset:512 sc1
	s_nop 1
	s_mov_b64 s[96:97], 0xa0000
	v_lshl_add_u64 v[146:147], v[132:133], 0, s[96:97]
	v_lshl_add_u64 v[148:149], v[136:137], 0, s[96:97]
	global_load_dwordx4 v[224:227], v[146:147], off sc1
	global_load_dwordx4 v[228:231], v[148:149], off sc1
	global_load_dwordx4 v[232:235], v[146:147], off offset:512 sc1
	global_load_dwordx4 v[236:239], v[148:149], off offset:512 sc1
	v_mov_b32_dpp v200, v70 quad_perm:[1,0,3,2] row_mask:0xf bank_mask:0xf
	v_cndmask_b32_dpp v201, v66, v200, vcc quad_perm:[1,0,3,2] row_mask:0xf bank_mask:0xf
	v_cndmask_b32_e32 v70, v201, v70, vcc
	v_cndmask_b32_e32 v66, v66, v201, vcc
	v_mov_b32_dpp v200, v71 quad_perm:[1,0,3,2] row_mask:0xf bank_mask:0xf
	v_cndmask_b32_dpp v201, v67, v200, vcc quad_perm:[1,0,3,2] row_mask:0xf bank_mask:0xf
	v_cndmask_b32_e32 v71, v201, v71, vcc
	v_cndmask_b32_e32 v67, v67, v201, vcc
	v_mov_b32_dpp v200, v72 quad_perm:[1,0,3,2] row_mask:0xf bank_mask:0xf
	v_cndmask_b32_dpp v201, v68, v200, vcc quad_perm:[1,0,3,2] row_mask:0xf bank_mask:0xf
	v_cndmask_b32_e32 v72, v201, v72, vcc
	v_cndmask_b32_e32 v68, v68, v201, vcc
	v_mov_b32_dpp v200, v73 quad_perm:[1,0,3,2] row_mask:0xf bank_mask:0xf
	v_cndmask_b32_dpp v201, v69, v200, vcc quad_perm:[1,0,3,2] row_mask:0xf bank_mask:0xf
	v_cndmask_b32_e32 v73, v201, v73, vcc
	v_cndmask_b32_e32 v69, v69, v201, vcc
	v_mov_b32_dpp v200, v78 quad_perm:[1,0,3,2] row_mask:0xf bank_mask:0xf
	v_cndmask_b32_dpp v201, v74, v200, vcc quad_perm:[1,0,3,2] row_mask:0xf bank_mask:0xf
	v_cndmask_b32_e32 v78, v201, v78, vcc
	v_cndmask_b32_e32 v74, v74, v201, vcc
	v_mov_b32_dpp v200, v79 quad_perm:[1,0,3,2] row_mask:0xf bank_mask:0xf
	v_cndmask_b32_dpp v201, v75, v200, vcc quad_perm:[1,0,3,2] row_mask:0xf bank_mask:0xf
	v_cndmask_b32_e32 v79, v201, v79, vcc
	v_cndmask_b32_e32 v75, v75, v201, vcc
	v_mov_b32_dpp v200, v80 quad_perm:[1,0,3,2] row_mask:0xf bank_mask:0xf
	v_cndmask_b32_dpp v201, v76, v200, vcc quad_perm:[1,0,3,2] row_mask:0xf bank_mask:0xf
	v_cndmask_b32_e32 v80, v201, v80, vcc
	v_cndmask_b32_e32 v76, v76, v201, vcc
	v_mov_b32_dpp v200, v81 quad_perm:[1,0,3,2] row_mask:0xf bank_mask:0xf
	v_cndmask_b32_dpp v201, v77, v200, vcc quad_perm:[1,0,3,2] row_mask:0xf bank_mask:0xf
	v_cndmask_b32_e32 v81, v201, v81, vcc
	v_cndmask_b32_e32 v77, v77, v201, vcc
	s_waitcnt vmcnt(24)
	v_pk_add_f32 v[240:241], v[70:71], v[240:241]
	v_pk_add_f32 v[242:243], v[72:73], v[242:243]
	v_pk_add_f32 v[244:245], v[66:67], v[244:245]
	v_pk_add_f32 v[246:247], v[68:69], v[246:247]
	v_pk_add_f32 v[248:249], v[78:79], v[248:249]
	v_pk_add_f32 v[250:251], v[80:81], v[250:251]
	v_pk_add_f32 v[206:207], v[74:75], v[206:207]
	v_pk_add_f32 v[208:209], v[76:77], v[208:209]
	v_lshl_add_u64 v[202:203], v[150:151], 0, s[98:99]
	v_lshl_add_u64 v[204:205], v[152:153], 0, s[98:99]
	global_store_dwordx4 v[202:203], v[240:243], off sc1
	global_store_dwordx4 v[204:205], v[244:247], off sc1
	global_store_dwordx4 v[202:203], v[248:251], off offset:512 sc1
	global_store_dwordx4 v[204:205], v[206:209], off offset:512 sc1
	s_nop 1
	s_mov_b64 s[96:97], 0xb0000
	v_lshl_add_u64 v[150:151], v[132:133], 0, s[96:97]
	v_lshl_add_u64 v[152:153], v[136:137], 0, s[96:97]
	global_load_dwordx4 v[240:243], v[150:151], off sc1
	global_load_dwordx4 v[244:247], v[152:153], off sc1
	global_load_dwordx4 v[248:251], v[150:151], off offset:512 sc1
	global_load_dwordx4 v[206:209], v[152:153], off offset:512 sc1
	v_mov_b32_dpp v200, v54 quad_perm:[1,0,3,2] row_mask:0xf bank_mask:0xf
	v_cndmask_b32_dpp v201, v50, v200, vcc quad_perm:[1,0,3,2] row_mask:0xf bank_mask:0xf
	v_cndmask_b32_e32 v54, v201, v54, vcc
	v_cndmask_b32_e32 v50, v50, v201, vcc
	v_mov_b32_dpp v200, v55 quad_perm:[1,0,3,2] row_mask:0xf bank_mask:0xf
	v_cndmask_b32_dpp v201, v51, v200, vcc quad_perm:[1,0,3,2] row_mask:0xf bank_mask:0xf
	v_cndmask_b32_e32 v55, v201, v55, vcc
	v_cndmask_b32_e32 v51, v51, v201, vcc
	v_mov_b32_dpp v200, v56 quad_perm:[1,0,3,2] row_mask:0xf bank_mask:0xf
	v_cndmask_b32_dpp v201, v52, v200, vcc quad_perm:[1,0,3,2] row_mask:0xf bank_mask:0xf
	v_cndmask_b32_e32 v56, v201, v56, vcc
	v_cndmask_b32_e32 v52, v52, v201, vcc
	v_mov_b32_dpp v200, v57 quad_perm:[1,0,3,2] row_mask:0xf bank_mask:0xf
	v_cndmask_b32_dpp v201, v53, v200, vcc quad_perm:[1,0,3,2] row_mask:0xf bank_mask:0xf
	v_cndmask_b32_e32 v57, v201, v57, vcc
	v_cndmask_b32_e32 v53, v53, v201, vcc
	v_mov_b32_dpp v200, v62 quad_perm:[1,0,3,2] row_mask:0xf bank_mask:0xf
	v_cndmask_b32_dpp v201, v58, v200, vcc quad_perm:[1,0,3,2] row_mask:0xf bank_mask:0xf
	v_cndmask_b32_e32 v62, v201, v62, vcc
	v_cndmask_b32_e32 v58, v58, v201, vcc
	v_mov_b32_dpp v200, v63 quad_perm:[1,0,3,2] row_mask:0xf bank_mask:0xf
	v_cndmask_b32_dpp v201, v59, v200, vcc quad_perm:[1,0,3,2] row_mask:0xf bank_mask:0xf
	v_cndmask_b32_e32 v63, v201, v63, vcc
	v_cndmask_b32_e32 v59, v59, v201, vcc
	v_mov_b32_dpp v200, v64 quad_perm:[1,0,3,2] row_mask:0xf bank_mask:0xf
	v_cndmask_b32_dpp v201, v60, v200, vcc quad_perm:[1,0,3,2] row_mask:0xf bank_mask:0xf
	v_cndmask_b32_e32 v64, v201, v64, vcc
	v_cndmask_b32_e32 v60, v60, v201, vcc
	v_mov_b32_dpp v200, v65 quad_perm:[1,0,3,2] row_mask:0xf bank_mask:0xf
	v_cndmask_b32_dpp v201, v61, v200, vcc quad_perm:[1,0,3,2] row_mask:0xf bank_mask:0xf
	v_cndmask_b32_e32 v65, v201, v65, vcc
	v_cndmask_b32_e32 v61, v61, v201, vcc
	s_waitcnt vmcnt(24)
;     ...
; #pragma unroll
;     for (int ai = 0; ai < 2; ++ai)
; #pragma unroll
;       for (int m = 0; m < 4; ++m)
;         epi(brow + ai * HALF + wr * 64 + m * 16 + fr, bcol + wc * 32, fq, acc[ai][0][m][0], acc[ai][0][m][1], acc[ai][1][m][0], acc[ai][1][m][1]);
	v_pk_add_f32 v[168:169], v[54:55], v[168:169]
	v_pk_add_f32 v[170:171], v[56:57], v[170:171]
	v_pk_add_f32 v[172:173], v[50:51], v[172:173]
	v_pk_add_f32 v[174:175], v[52:53], v[174:175]
	v_pk_add_f32 v[176:177], v[62:63], v[176:177]
	v_pk_add_f32 v[178:179], v[64:65], v[178:179]
	v_pk_add_f32 v[180:181], v[58:59], v[180:181]
	v_pk_add_f32 v[182:183], v[60:61], v[182:183]
	v_lshl_add_u64 v[202:203], v[138:139], 0, s[98:99]
	v_lshl_add_u64 v[204:205], v[140:141], 0, s[98:99]
	global_store_dwordx4 v[202:203], v[168:171], off sc1
	global_store_dwordx4 v[204:205], v[172:175], off sc1
	global_store_dwordx4 v[202:203], v[176:179], off offset:512 sc1
	global_store_dwordx4 v[204:205], v[180:183], off offset:512 sc1
	v_mov_b32_dpp v200, v38 quad_perm:[1,0,3,2] row_mask:0xf bank_mask:0xf
	v_cndmask_b32_dpp v201, v34, v200, vcc quad_perm:[1,0,3,2] row_mask:0xf bank_mask:0xf
	v_cndmask_b32_e32 v38, v201, v38, vcc
	v_cndmask_b32_e32 v34, v34, v201, vcc
	v_mov_b32_dpp v200, v39 quad_perm:[1,0,3,2] row_mask:0xf bank_mask:0xf
	v_cndmask_b32_dpp v201, v35, v200, vcc quad_perm:[1,0,3,2] row_mask:0xf bank_mask:0xf
	v_cndmask_b32_e32 v39, v201, v39, vcc
	v_cndmask_b32_e32 v35, v35, v201, vcc
	v_mov_b32_dpp v200, v40 quad_perm:[1,0,3,2] row_mask:0xf bank_mask:0xf
	v_cndmask_b32_dpp v201, v36, v200, vcc quad_perm:[1,0,3,2] row_mask:0xf bank_mask:0xf
	v_cndmask_b32_e32 v40, v201, v40, vcc
	v_cndmask_b32_e32 v36, v36, v201, vcc
	v_mov_b32_dpp v200, v41 quad_perm:[1,0,3,2] row_mask:0xf bank_mask:0xf
	v_cndmask_b32_dpp v201, v37, v200, vcc quad_perm:[1,0,3,2] row_mask:0xf bank_mask:0xf
	v_cndmask_b32_e32 v41, v201, v41, vcc
	v_cndmask_b32_e32 v37, v37, v201, vcc
	v_mov_b32_dpp v200, v46 quad_perm:[1,0,3,2] row_mask:0xf bank_mask:0xf
	v_cndmask_b32_dpp v201, v42, v200, vcc quad_perm:[1,0,3,2] row_mask:0xf bank_mask:0xf
	v_cndmask_b32_e32 v46, v201, v46, vcc
	v_cndmask_b32_e32 v42, v42, v201, vcc
	v_mov_b32_dpp v200, v47 quad_perm:[1,0,3,2] row_mask:0xf bank_mask:0xf
	v_cndmask_b32_dpp v201, v43, v200, vcc quad_perm:[1,0,3,2] row_mask:0xf bank_mask:0xf
	v_cndmask_b32_e32 v47, v201, v47, vcc
	v_cndmask_b32_e32 v43, v43, v201, vcc
	v_mov_b32_dpp v200, v48 quad_perm:[1,0,3,2] row_mask:0xf bank_mask:0xf
	v_cndmask_b32_dpp v201, v44, v200, vcc quad_perm:[1,0,3,2] row_mask:0xf bank_mask:0xf
	v_cndmask_b32_e32 v48, v201, v48, vcc
	v_cndmask_b32_e32 v44, v44, v201, vcc
	v_mov_b32_dpp v200, v49 quad_perm:[1,0,3,2] row_mask:0xf bank_mask:0xf
	v_cndmask_b32_dpp v201, v45, v200, vcc quad_perm:[1,0,3,2] row_mask:0xf bank_mask:0xf
	v_cndmask_b32_e32 v49, v201, v49, vcc
	v_cndmask_b32_e32 v45, v45, v201, vcc
	s_waitcnt vmcnt(20)
	v_pk_add_f32 v[184:185], v[38:39], v[184:185]
	v_pk_add_f32 v[186:187], v[40:41], v[186:187]
	v_pk_add_f32 v[188:189], v[34:35], v[188:189]
	v_pk_add_f32 v[190:191], v[36:37], v[190:191]
	v_pk_add_f32 v[192:193], v[46:47], v[192:193]
	v_pk_add_f32 v[194:195], v[48:49], v[194:195]
	v_pk_add_f32 v[196:197], v[42:43], v[196:197]
	v_pk_add_f32 v[198:199], v[44:45], v[198:199]
	v_lshl_add_u64 v[202:203], v[142:143], 0, s[98:99]
	v_lshl_add_u64 v[204:205], v[144:145], 0, s[98:99]
	global_store_dwordx4 v[202:203], v[184:187], off sc1
	global_store_dwordx4 v[204:205], v[188:191], off sc1
	global_store_dwordx4 v[202:203], v[192:195], off offset:512 sc1
	global_store_dwordx4 v[204:205], v[196:199], off offset:512 sc1
	v_mov_b32_dpp v200, v22 quad_perm:[1,0,3,2] row_mask:0xf bank_mask:0xf
	v_cndmask_b32_dpp v201, v220, v200, vcc quad_perm:[1,0,3,2] row_mask:0xf bank_mask:0xf
	v_cndmask_b32_e32 v22, v201, v22, vcc
	v_cndmask_b32_e32 v220, v220, v201, vcc
	v_mov_b32_dpp v200, v23 quad_perm:[1,0,3,2] row_mask:0xf bank_mask:0xf
	v_cndmask_b32_dpp v201, v221, v200, vcc quad_perm:[1,0,3,2] row_mask:0xf bank_mask:0xf
	v_cndmask_b32_e32 v23, v201, v23, vcc
	v_cndmask_b32_e32 v221, v221, v201, vcc
	v_mov_b32_dpp v200, v24 quad_perm:[1,0,3,2] row_mask:0xf bank_mask:0xf
	v_cndmask_b32_dpp v201, v222, v200, vcc quad_perm:[1,0,3,2] row_mask:0xf bank_mask:0xf
	v_cndmask_b32_e32 v24, v201, v24, vcc
	v_cndmask_b32_e32 v222, v222, v201, vcc
	v_mov_b32_dpp v200, v25 quad_perm:[1,0,3,2] row_mask:0xf bank_mask:0xf
	v_cndmask_b32_dpp v201, v223, v200, vcc quad_perm:[1,0,3,2] row_mask:0xf bank_mask:0xf
	v_cndmask_b32_e32 v25, v201, v25, vcc
	v_cndmask_b32_e32 v223, v223, v201, vcc
	v_mov_b32_dpp v200, v30 quad_perm:[1,0,3,2] row_mask:0xf bank_mask:0xf
	v_cndmask_b32_dpp v201, v26, v200, vcc quad_perm:[1,0,3,2] row_mask:0xf bank_mask:0xf
	v_cndmask_b32_e32 v30, v201, v30, vcc
	v_cndmask_b32_e32 v26, v26, v201, vcc
	v_mov_b32_dpp v200, v31 quad_perm:[1,0,3,2] row_mask:0xf bank_mask:0xf
	v_cndmask_b32_dpp v201, v27, v200, vcc quad_perm:[1,0,3,2] row_mask:0xf bank_mask:0xf
	v_cndmask_b32_e32 v31, v201, v31, vcc
	v_cndmask_b32_e32 v27, v27, v201, vcc
	v_mov_b32_dpp v200, v32 quad_perm:[1,0,3,2] row_mask:0xf bank_mask:0xf
	v_cndmask_b32_dpp v201, v28, v200, vcc quad_perm:[1,0,3,2] row_mask:0xf bank_mask:0xf
	v_cndmask_b32_e32 v32, v201, v32, vcc
	v_cndmask_b32_e32 v28, v28, v201, vcc
	v_mov_b32_dpp v200, v33 quad_perm:[1,0,3,2] row_mask:0xf bank_mask:0xf
	v_cndmask_b32_dpp v201, v29, v200, vcc quad_perm:[1,0,3,2] row_mask:0xf bank_mask:0xf
	v_cndmask_b32_e32 v33, v201, v33, vcc
	v_cndmask_b32_e32 v29, v29, v201, vcc
	s_waitcnt vmcnt(16)
; #define WAIT_V(n) asm volatile("s_waitcnt vmcnt(" #n ")" ::: "memory")
;     ...
;   if (!have_next) { WAIT_V(0); __syncthreads(); }
	v_pk_add_f32 v[224:225], v[22:23], v[224:225]
	v_pk_add_f32 v[226:227], v[24:25], v[226:227]
	v_pk_add_f32 v[228:229], v[220:221], v[228:229]
	v_pk_add_f32 v[230:231], v[222:223], v[230:231]
	v_pk_add_f32 v[232:233], v[30:31], v[232:233]
	v_pk_add_f32 v[234:235], v[32:33], v[234:235]
	v_pk_add_f32 v[236:237], v[26:27], v[236:237]
	v_pk_add_f32 v[238:239], v[28:29], v[238:239]
	v_lshl_add_u64 v[202:203], v[146:147], 0, s[98:99]
	v_lshl_add_u64 v[204:205], v[148:149], 0, s[98:99]
	global_store_dwordx4 v[202:203], v[224:227], off sc1
	global_store_dwordx4 v[204:205], v[228:231], off sc1
	global_store_dwordx4 v[202:203], v[232:235], off offset:512 sc1
	global_store_dwordx4 v[204:205], v[236:239], off offset:512 sc1
	v_mov_b32_dpp v200, v6 quad_perm:[1,0,3,2] row_mask:0xf bank_mask:0xf
	v_cndmask_b32_dpp v201, v2, v200, vcc quad_perm:[1,0,3,2] row_mask:0xf bank_mask:0xf
	v_cndmask_b32_e32 v6, v201, v6, vcc
	v_cndmask_b32_e32 v2, v2, v201, vcc
	v_mov_b32_dpp v200, v7 quad_perm:[1,0,3,2] row_mask:0xf bank_mask:0xf
	v_cndmask_b32_dpp v201, v3, v200, vcc quad_perm:[1,0,3,2] row_mask:0xf bank_mask:0xf
	v_cndmask_b32_e32 v7, v201, v7, vcc
	v_cndmask_b32_e32 v3, v3, v201, vcc
	v_mov_b32_dpp v200, v8 quad_perm:[1,0,3,2] row_mask:0xf bank_mask:0xf
	v_cndmask_b32_dpp v201, v4, v200, vcc quad_perm:[1,0,3,2] row_mask:0xf bank_mask:0xf
	v_cndmask_b32_e32 v8, v201, v8, vcc
	v_cndmask_b32_e32 v4, v4, v201, vcc
	v_mov_b32_dpp v200, v9 quad_perm:[1,0,3,2] row_mask:0xf bank_mask:0xf
	v_cndmask_b32_dpp v201, v5, v200, vcc quad_perm:[1,0,3,2] row_mask:0xf bank_mask:0xf
	v_cndmask_b32_e32 v9, v201, v9, vcc
	v_cndmask_b32_e32 v5, v5, v201, vcc
	v_mov_b32_dpp v200, v14 quad_perm:[1,0,3,2] row_mask:0xf bank_mask:0xf
	v_cndmask_b32_dpp v201, v10, v200, vcc quad_perm:[1,0,3,2] row_mask:0xf bank_mask:0xf
	v_cndmask_b32_e32 v14, v201, v14, vcc
	v_cndmask_b32_e32 v10, v10, v201, vcc
	v_mov_b32_dpp v200, v15 quad_perm:[1,0,3,2] row_mask:0xf bank_mask:0xf
	v_cndmask_b32_dpp v201, v11, v200, vcc quad_perm:[1,0,3,2] row_mask:0xf bank_mask:0xf
	v_cndmask_b32_e32 v15, v201, v15, vcc
	v_cndmask_b32_e32 v11, v11, v201, vcc
	v_mov_b32_dpp v200, v16 quad_perm:[1,0,3,2] row_mask:0xf bank_mask:0xf
	v_cndmask_b32_dpp v201, v12, v200, vcc quad_perm:[1,0,3,2] row_mask:0xf bank_mask:0xf
	v_cndmask_b32_e32 v16, v201, v16, vcc
	v_cndmask_b32_e32 v12, v12, v201, vcc
	v_mov_b32_dpp v200, v17 quad_perm:[1,0,3,2] row_mask:0xf bank_mask:0xf
	v_cndmask_b32_dpp v201, v13, v200, vcc quad_perm:[1,0,3,2] row_mask:0xf bank_mask:0xf
	v_cndmask_b32_e32 v17, v201, v17, vcc
	v_cndmask_b32_e32 v13, v13, v201, vcc
	s_waitcnt vmcnt(12)
	v_pk_add_f32 v[240:241], v[6:7], v[240:241]
	v_pk_add_f32 v[242:243], v[8:9], v[242:243]
	v_pk_add_f32 v[244:245], v[2:3], v[244:245]
	v_pk_add_f32 v[246:247], v[4:5], v[246:247]
	v_pk_add_f32 v[248:249], v[14:15], v[248:249]
	v_pk_add_f32 v[250:251], v[16:17], v[250:251]
	v_pk_add_f32 v[206:207], v[10:11], v[206:207]
	v_pk_add_f32 v[208:209], v[12:13], v[208:209]
	v_lshl_add_u64 v[202:203], v[150:151], 0, s[98:99]
	v_lshl_add_u64 v[204:205], v[152:153], 0, s[98:99]
	global_store_dwordx4 v[202:203], v[240:243], off sc1
	global_store_dwordx4 v[204:205], v[244:247], off sc1
	global_store_dwordx4 v[202:203], v[248:251], off offset:512 sc1
	global_store_dwordx4 v[204:205], v[206:209], off offset:512 sc1
	s_andn2_b64 vcc, exec, s[4:5]
	s_cbranch_vccnz .LBB0_1474
	s_waitcnt vmcnt(0)
	s_waitcnt lgkmcnt(0)
	s_barrier
	s_branch .LBB0_1474

;     ...
; #pragma unroll
;     for (int ai = 0; ai < 2; ++ai)
; #pragma unroll
;       for (int m = 0; m < 4; ++m)
;         epi(brow + ai * HALF + wr * 64 + m * 16 + fr, bcol + wc * 32, fq, acc[ai][0][m][0], acc[ai][0][m][1], acc[ai][1][m][0], acc[ai][1][m][1]);
.LBB0_1564:
	v_or_b32_e32 v0, s16, v140
	v_add_u32_e32 v136, v0, v141
	v_ashrrev_i32_e32 v137, 31, v136
	v_readlane_b32 s4, v253, 60
	v_lshl_or_b32 v0, v139, 5, s15
	v_lshlrev_b64 v[132:133], 12, v[136:137]
	v_readlane_b32 s5, v253, 61
	v_lshlrev_b64 v[134:135], 2, v[0:1]
	v_mov_b32_e32 v131, v1
	v_lshl_add_u64 v[132:133], s[4:5], 0, v[132:133]
	v_lshl_add_u64 v[132:133], v[132:133], 0, v[134:135]
	v_lshl_add_u64 v[132:133], v[132:133], 0, v[130:131]
	v_cndmask_b32_e64 v0, 0, 1, s[2:3]
	v_and_b32_e32 v134, 1, v210
	v_cmp_eq_u32_e32 vcc, 0, v134
	s_nop 1
	v_mov_b32_e32 v135, 0xfffff040
	v_cndmask_b32_e32 v134, v135, v1, vcc
	v_cndmask_b32_e32 v135, -1, v1, vcc
	v_lshl_add_u64 v[132:133], v[132:133], 0, v[134:135]
	s_mov_b64 s[4:5], 0x1000
	v_lshl_add_u64 v[136:137], v[132:133], 0, s[4:5]
	v_mov_b64_e32 v[138:139], v[132:133]
	v_mov_b64_e32 v[140:141], v[136:137]
	global_load_dwordx4 v[168:171], v[138:139], off sc1
	global_load_dwordx4 v[172:175], v[140:141], off sc1
	global_load_dwordx4 v[176:179], v[138:139], off offset:512 sc1
	global_load_dwordx4 v[180:183], v[140:141], off offset:512 sc1
	s_mov_b64 s[4:5], 0x10000
	v_lshl_add_u64 v[142:143], v[132:133], 0, s[4:5]
	v_lshl_add_u64 v[144:145], v[136:137], 0, s[4:5]
	global_load_dwordx4 v[184:187], v[142:143], off sc1
	global_load_dwordx4 v[188:191], v[144:145], off sc1
	global_load_dwordx4 v[192:195], v[142:143], off offset:512 sc1
	global_load_dwordx4 v[196:199], v[144:145], off offset:512 sc1
	s_mov_b64 s[4:5], 0x20000
	v_lshl_add_u64 v[146:147], v[132:133], 0, s[4:5]
	v_lshl_add_u64 v[148:149], v[136:137], 0, s[4:5]
	global_load_dwordx4 v[220:223], v[146:147], off sc1
	global_load_dwordx4 v[224:227], v[148:149], off sc1
	global_load_dwordx4 v[228:231], v[146:147], off offset:512 sc1
	global_load_dwordx4 v[232:235], v[148:149], off offset:512 sc1
	s_mov_b64 s[4:5], 0x30000
	v_lshl_add_u64 v[150:151], v[132:133], 0, s[4:5]
	v_lshl_add_u64 v[152:153], v[136:137], 0, s[4:5]
	global_load_dwordx4 v[236:239], v[150:151], off sc1
	global_load_dwordx4 v[240:243], v[152:153], off sc1
	global_load_dwordx4 v[244:247], v[150:151], off offset:512 sc1
	global_load_dwordx4 v[248:251], v[152:153], off offset:512 sc1
	v_mov_b32_dpp v200, v118 quad_perm:[1,0,3,2] row_mask:0xf bank_mask:0xf
	v_cndmask_b32_dpp v201, v114, v200, vcc quad_perm:[1,0,3,2] row_mask:0xf bank_mask:0xf
	v_cndmask_b32_e32 v118, v201, v118, vcc
	v_cndmask_b32_e32 v114, v114, v201, vcc
	v_mov_b32_dpp v200, v119 quad_perm:[1,0,3,2] row_mask:0xf bank_mask:0xf
	v_cndmask_b32_dpp v201, v115, v200, vcc quad_perm:[1,0,3,2] row_mask:0xf bank_mask:0xf
	v_cndmask_b32_e32 v119, v201, v119, vcc
	v_cndmask_b32_e32 v115, v115, v201, vcc
	v_mov_b32_dpp v200, v120 quad_perm:[1,0,3,2] row_mask:0xf bank_mask:0xf
	v_cndmask_b32_dpp v201, v116, v200, vcc quad_perm:[1,0,3,2] row_mask:0xf bank_mask:0xf
	v_cndmask_b32_e32 v120, v201, v120, vcc
	v_cndmask_b32_e32 v116, v116, v201, vcc
	v_mov_b32_dpp v200, v121 quad_perm:[1,0,3,2] row_mask:0xf bank_mask:0xf
	v_cndmask_b32_dpp v201, v117, v200, vcc quad_perm:[1,0,3,2] row_mask:0xf bank_mask:0xf
	v_cndmask_b32_e32 v121, v201, v121, vcc
	v_cndmask_b32_e32 v117, v117, v201, vcc
	v_mov_b32_dpp v200, v126 quad_perm:[1,0,3,2] row_mask:0xf bank_mask:0xf
	v_cndmask_b32_dpp v201, v122, v200, vcc quad_perm:[1,0,3,2] row_mask:0xf bank_mask:0xf
	v_cndmask_b32_e32 v126, v201, v126, vcc
	v_cndmask_b32_e32 v122, v122, v201, vcc
	v_mov_b32_dpp v200, v127 quad_perm:[1,0,3,2] row_mask:0xf bank_mask:0xf
	v_cndmask_b32_dpp v201, v123, v200, vcc quad_perm:[1,0,3,2] row_mask:0xf bank_mask:0xf
	v_cndmask_b32_e32 v127, v201, v127, vcc
	v_cndmask_b32_e32 v123, v123, v201, vcc
	v_mov_b32_dpp v200, v128 quad_perm:[1,0,3,2] row_mask:0xf bank_mask:0xf
	v_cndmask_b32_dpp v201, v124, v200, vcc quad_perm:[1,0,3,2] row_mask:0xf bank_mask:0xf
	v_cndmask_b32_e32 v128, v201, v128, vcc
	v_cndmask_b32_e32 v124, v124, v201, vcc
	v_mov_b32_dpp v200, v129 quad_perm:[1,0,3,2] row_mask:0xf bank_mask:0xf
	v_cndmask_b32_dpp v201, v125, v200, vcc quad_perm:[1,0,3,2] row_mask:0xf bank_mask:0xf
	v_cndmask_b32_e32 v129, v201, v129, vcc
	v_cndmask_b32_e32 v125, v125, v201, vcc
	s_waitcnt vmcnt(12)
	v_pk_add_f32 v[168:169], v[118:119], v[168:169]
	v_pk_add_f32 v[170:171], v[120:121], v[170:171]
	v_pk_add_f32 v[172:173], v[114:115], v[172:173]
	v_pk_add_f32 v[174:175], v[116:117], v[174:175]
	v_pk_add_f32 v[176:177], v[126:127], v[176:177]
	v_pk_add_f32 v[178:179], v[128:129], v[178:179]
	v_pk_add_f32 v[180:181], v[122:123], v[180:181]
	v_pk_add_f32 v[182:183], v[124:125], v[182:183]
	global_store_dwordx4 v[138:139], v[168:171], off sc1
	global_store_dwordx4 v[140:141], v[172:175], off sc1
	global_store_dwordx4 v[138:139], v[176:179], off offset:512 sc1
	global_store_dwordx4 v[140:141], v[180:183], off offset:512 sc1
	s_nop 1
	s_mov_b64 s[4:5], 0x80000
	v_lshl_add_u64 v[138:139], v[132:133], 0, s[4:5]
	v_lshl_add_u64 v[140:141], v[136:137], 0, s[4:5]
	global_load_dwordx4 v[168:171], v[138:139], off sc1
	global_load_dwordx4 v[172:175], v[140:141], off sc1
	global_load_dwordx4 v[176:179], v[138:139], off offset:512 sc1
	global_load_dwordx4 v[180:183], v[140:141], off offset:512 sc1
	v_mov_b32_dpp v200, v102 quad_perm:[1,0,3,2] row_mask:0xf bank_mask:0xf
	v_cndmask_b32_dpp v201, v98, v200, vcc quad_perm:[1,0,3,2] row_mask:0xf bank_mask:0xf
	v_cndmask_b32_e32 v102, v201, v102, vcc
	v_cndmask_b32_e32 v98, v98, v201, vcc
	v_mov_b32_dpp v200, v103 quad_perm:[1,0,3,2] row_mask:0xf bank_mask:0xf
	v_cndmask_b32_dpp v201, v99, v200, vcc quad_perm:[1,0,3,2] row_mask:0xf bank_mask:0xf
	v_cndmask_b32_e32 v103, v201, v103, vcc
	v_cndmask_b32_e32 v99, v99, v201, vcc
;     ...
; #pragma unroll
;     for (int ai = 0; ai < 2; ++ai)
; #pragma unroll
;       for (int m = 0; m < 4; ++m)
;         epi(brow + ai * HALF + wr * 64 + m * 16 + fr, bcol + wc * 32, fq, acc[ai][0][m][0], acc[ai][0][m][1], acc[ai][1][m][0], acc[ai][1][m][1]);
	v_mov_b32_dpp v200, v104 quad_perm:[1,0,3,2] row_mask:0xf bank_mask:0xf
	v_cndmask_b32_dpp v201, v100, v200, vcc quad_perm:[1,0,3,2] row_mask:0xf bank_mask:0xf
	v_cndmask_b32_e32 v104, v201, v104, vcc
	v_cndmask_b32_e32 v100, v100, v201, vcc
	v_mov_b32_dpp v200, v105 quad_perm:[1,0,3,2] row_mask:0xf bank_mask:0xf
	v_cndmask_b32_dpp v201, v101, v200, vcc quad_perm:[1,0,3,2] row_mask:0xf bank_mask:0xf
	v_cndmask_b32_e32 v105, v201, v105, vcc
	v_cndmask_b32_e32 v101, v101, v201, vcc
	v_mov_b32_dpp v200, v110 quad_perm:[1,0,3,2] row_mask:0xf bank_mask:0xf
	v_cndmask_b32_dpp v201, v106, v200, vcc quad_perm:[1,0,3,2] row_mask:0xf bank_mask:0xf
	v_cndmask_b32_e32 v110, v201, v110, vcc
	v_cndmask_b32_e32 v106, v106, v201, vcc
	v_mov_b32_dpp v200, v111 quad_perm:[1,0,3,2] row_mask:0xf bank_mask:0xf
	v_cndmask_b32_dpp v201, v107, v200, vcc quad_perm:[1,0,3,2] row_mask:0xf bank_mask:0xf
	v_cndmask_b32_e32 v111, v201, v111, vcc
	v_cndmask_b32_e32 v107, v107, v201, vcc
	v_mov_b32_dpp v200, v112 quad_perm:[1,0,3,2] row_mask:0xf bank_mask:0xf
	v_cndmask_b32_dpp v201, v108, v200, vcc quad_perm:[1,0,3,2] row_mask:0xf bank_mask:0xf
	v_cndmask_b32_e32 v112, v201, v112, vcc
	v_cndmask_b32_e32 v108, v108, v201, vcc
	v_mov_b32_dpp v200, v113 quad_perm:[1,0,3,2] row_mask:0xf bank_mask:0xf
	v_cndmask_b32_dpp v201, v109, v200, vcc quad_perm:[1,0,3,2] row_mask:0xf bank_mask:0xf
	v_cndmask_b32_e32 v113, v201, v113, vcc
	v_cndmask_b32_e32 v109, v109, v201, vcc
	s_waitcnt vmcnt(16)
	v_pk_add_f32 v[184:185], v[102:103], v[184:185]
	v_pk_add_f32 v[186:187], v[104:105], v[186:187]
	v_pk_add_f32 v[188:189], v[98:99], v[188:189]
	v_pk_add_f32 v[190:191], v[100:101], v[190:191]
	v_pk_add_f32 v[192:193], v[110:111], v[192:193]
	v_pk_add_f32 v[194:195], v[112:113], v[194:195]
	v_pk_add_f32 v[196:197], v[106:107], v[196:197]
	v_pk_add_f32 v[198:199], v[108:109], v[198:199]
	global_store_dwordx4 v[142:143], v[184:187], off sc1
	global_store_dwordx4 v[144:145], v[188:191], off sc1
	global_store_dwordx4 v[142:143], v[192:195], off offset:512 sc1
	global_store_dwordx4 v[144:145], v[196:199], off offset:512 sc1
	s_nop 1
	s_mov_b64 s[4:5], 0x90000
	v_lshl_add_u64 v[142:143], v[132:133], 0, s[4:5]
	v_lshl_add_u64 v[144:145], v[136:137], 0, s[4:5]
	global_load_dwordx4 v[184:187], v[142:143], off sc1
	global_load_dwordx4 v[188:191], v[144:145], off sc1
	global_load_dwordx4 v[192:195], v[142:143], off offset:512 sc1
	global_load_dwordx4 v[196:199], v[144:145], off offset:512 sc1
	v_mov_b32_dpp v200, v86 quad_perm:[1,0,3,2] row_mask:0xf bank_mask:0xf
	v_cndmask_b32_dpp v201, v82, v200, vcc quad_perm:[1,0,3,2] row_mask:0xf bank_mask:0xf
	v_cndmask_b32_e32 v86, v201, v86, vcc
	v_cndmask_b32_e32 v82, v82, v201, vcc
	v_mov_b32_dpp v200, v87 quad_perm:[1,0,3,2] row_mask:0xf bank_mask:0xf
	v_cndmask_b32_dpp v201, v83, v200, vcc quad_perm:[1,0,3,2] row_mask:0xf bank_mask:0xf
	v_cndmask_b32_e32 v87, v201, v87, vcc
	v_cndmask_b32_e32 v83, v83, v201, vcc
	v_mov_b32_dpp v200, v88 quad_perm:[1,0,3,2] row_mask:0xf bank_mask:0xf
	v_cndmask_b32_dpp v201, v84, v200, vcc quad_perm:[1,0,3,2] row_mask:0xf bank_mask:0xf
	v_cndmask_b32_e32 v88, v201, v88, vcc
	v_cndmask_b32_e32 v84, v84, v201, vcc
	v_mov_b32_dpp v200, v89 quad_perm:[1,0,3,2] row_mask:0xf bank_mask:0xf
	v_cndmask_b32_dpp v201, v85, v200, vcc quad_perm:[1,0,3,2] row_mask:0xf bank_mask:0xf
	v_cndmask_b32_e32 v89, v201, v89, vcc
	v_cndmask_b32_e32 v85, v85, v201, vcc
	v_mov_b32_dpp v200, v94 quad_perm:[1,0,3,2] row_mask:0xf bank_mask:0xf
	v_cndmask_b32_dpp v201, v90, v200, vcc quad_perm:[1,0,3,2] row_mask:0xf bank_mask:0xf
	v_cndmask_b32_e32 v94, v201, v94, vcc
	v_cndmask_b32_e32 v90, v90, v201, vcc
	v_mov_b32_dpp v200, v95 quad_perm:[1,0,3,2] row_mask:0xf bank_mask:0xf
	v_cndmask_b32_dpp v201, v91, v200, vcc quad_perm:[1,0,3,2] row_mask:0xf bank_mask:0xf
	v_cndmask_b32_e32 v95, v201, v95, vcc
	v_cndmask_b32_e32 v91, v91, v201, vcc
	v_mov_b32_dpp v200, v96 quad_perm:[1,0,3,2] row_mask:0xf bank_mask:0xf
	v_cndmask_b32_dpp v201, v92, v200, vcc quad_perm:[1,0,3,2] row_mask:0xf bank_mask:0xf
	v_cndmask_b32_e32 v96, v201, v96, vcc
	v_cndmask_b32_e32 v92, v92, v201, vcc
	v_mov_b32_dpp v200, v97 quad_perm:[1,0,3,2] row_mask:0xf bank_mask:0xf
	v_cndmask_b32_dpp v201, v93, v200, vcc quad_perm:[1,0,3,2] row_mask:0xf bank_mask:0xf
	v_cndmask_b32_e32 v97, v201, v97, vcc
	v_cndmask_b32_e32 v93, v93, v201, vcc
	s_waitcnt vmcnt(20)
;     ...
; #pragma unroll
;     for (int ai = 0; ai < 2; ++ai)
; #pragma unroll
;       for (int m = 0; m < 4; ++m)
;         epi(brow + ai * HALF + wr * 64 + m * 16 + fr, bcol + wc * 32, fq, acc[ai][0][m][0], acc[ai][0][m][1], acc[ai][1][m][0], acc[ai][1][m][1]);
	v_pk_add_f32 v[220:221], v[86:87], v[220:221]
	v_pk_add_f32 v[222:223], v[88:89], v[222:223]
	v_pk_add_f32 v[224:225], v[82:83], v[224:225]
	v_pk_add_f32 v[226:227], v[84:85], v[226:227]
	v_pk_add_f32 v[228:229], v[94:95], v[228:229]
	v_pk_add_f32 v[230:231], v[96:97], v[230:231]
	v_pk_add_f32 v[232:233], v[90:91], v[232:233]
	v_pk_add_f32 v[234:235], v[92:93], v[234:235]
	global_store_dwordx4 v[146:147], v[220:223], off sc1
	global_store_dwordx4 v[148:149], v[224:227], off sc1
	global_store_dwordx4 v[146:147], v[228:231], off offset:512 sc1
	global_store_dwordx4 v[148:149], v[232:235], off offset:512 sc1
	s_nop 1
	s_mov_b64 s[4:5], 0xa0000
	v_lshl_add_u64 v[146:147], v[132:133], 0, s[4:5]
	v_lshl_add_u64 v[148:149], v[136:137], 0, s[4:5]
	global_load_dwordx4 v[220:223], v[146:147], off sc1
	global_load_dwordx4 v[224:227], v[148:149], off sc1
	global_load_dwordx4 v[228:231], v[146:147], off offset:512 sc1
	global_load_dwordx4 v[232:235], v[148:149], off offset:512 sc1
	v_mov_b32_dpp v200, v70 quad_perm:[1,0,3,2] row_mask:0xf bank_mask:0xf
	v_cndmask_b32_dpp v201, v66, v200, vcc quad_perm:[1,0,3,2] row_mask:0xf bank_mask:0xf
	v_cndmask_b32_e32 v70, v201, v70, vcc
	v_cndmask_b32_e32 v66, v66, v201, vcc
	v_mov_b32_dpp v200, v71 quad_perm:[1,0,3,2] row_mask:0xf bank_mask:0xf
	v_cndmask_b32_dpp v201, v67, v200, vcc quad_perm:[1,0,3,2] row_mask:0xf bank_mask:0xf
	v_cndmask_b32_e32 v71, v201, v71, vcc
	v_cndmask_b32_e32 v67, v67, v201, vcc
	v_mov_b32_dpp v200, v72 quad_perm:[1,0,3,2] row_mask:0xf bank_mask:0xf
	v_cndmask_b32_dpp v201, v68, v200, vcc quad_perm:[1,0,3,2] row_mask:0xf bank_mask:0xf
	v_cndmask_b32_e32 v72, v201, v72, vcc
	v_cndmask_b32_e32 v68, v68, v201, vcc
	v_mov_b32_dpp v200, v73 quad_perm:[1,0,3,2] row_mask:0xf bank_mask:0xf
	v_cndmask_b32_dpp v201, v69, v200, vcc quad_perm:[1,0,3,2] row_mask:0xf bank_mask:0xf
	v_cndmask_b32_e32 v73, v201, v73, vcc
	v_cndmask_b32_e32 v69, v69, v201, vcc
	v_mov_b32_dpp v200, v78 quad_perm:[1,0,3,2] row_mask:0xf bank_mask:0xf
	v_cndmask_b32_dpp v201, v74, v200, vcc quad_perm:[1,0,3,2] row_mask:0xf bank_mask:0xf
	v_cndmask_b32_e32 v78, v201, v78, vcc
	v_cndmask_b32_e32 v74, v74, v201, vcc
	v_mov_b32_dpp v200, v79 quad_perm:[1,0,3,2] row_mask:0xf bank_mask:0xf
	v_cndmask_b32_dpp v201, v75, v200, vcc quad_perm:[1,0,3,2] row_mask:0xf bank_mask:0xf
	v_cndmask_b32_e32 v79, v201, v79, vcc
	v_cndmask_b32_e32 v75, v75, v201, vcc
	v_mov_b32_dpp v200, v80 quad_perm:[1,0,3,2] row_mask:0xf bank_mask:0xf
	v_cndmask_b32_dpp v201, v76, v200, vcc quad_perm:[1,0,3,2] row_mask:0xf bank_mask:0xf
	v_cndmask_b32_e32 v80, v201, v80, vcc
	v_cndmask_b32_e32 v76, v76, v201, vcc
	v_mov_b32_dpp v200, v81 quad_perm:[1,0,3,2] row_mask:0xf bank_mask:0xf
	v_cndmask_b32_dpp v201, v77, v200, vcc quad_perm:[1,0,3,2] row_mask:0xf bank_mask:0xf
	v_cndmask_b32_e32 v81, v201, v81, vcc
	v_cndmask_b32_e32 v77, v77, v201, vcc
	s_waitcnt vmcnt(24)
	v_pk_add_f32 v[236:237], v[70:71], v[236:237]
	v_pk_add_f32 v[238:239], v[72:73], v[238:239]
	v_pk_add_f32 v[240:241], v[66:67], v[240:241]
	v_pk_add_f32 v[242:243], v[68:69], v[242:243]
	v_pk_add_f32 v[244:245], v[78:79], v[244:245]
	v_pk_add_f32 v[246:247], v[80:81], v[246:247]
	v_pk_add_f32 v[248:249], v[74:75], v[248:249]
	v_pk_add_f32 v[250:251], v[76:77], v[250:251]
	global_store_dwordx4 v[150:151], v[236:239], off sc1
	global_store_dwordx4 v[152:153], v[240:243], off sc1
	global_store_dwordx4 v[150:151], v[244:247], off offset:512 sc1
	global_store_dwordx4 v[152:153], v[248:251], off offset:512 sc1
	s_nop 1
	s_mov_b64 s[4:5], 0xb0000
	v_lshl_add_u64 v[150:151], v[132:133], 0, s[4:5]
	v_lshl_add_u64 v[152:153], v[136:137], 0, s[4:5]
	global_load_dwordx4 v[236:239], v[150:151], off sc1
	global_load_dwordx4 v[240:243], v[152:153], off sc1
	global_load_dwordx4 v[244:247], v[150:151], off offset:512 sc1
	global_load_dwordx4 v[248:251], v[152:153], off offset:512 sc1
	v_mov_b32_dpp v200, v54 quad_perm:[1,0,3,2] row_mask:0xf bank_mask:0xf
	v_cndmask_b32_dpp v201, v50, v200, vcc quad_perm:[1,0,3,2] row_mask:0xf bank_mask:0xf
	v_cndmask_b32_e32 v54, v201, v54, vcc
	v_cndmask_b32_e32 v50, v50, v201, vcc
	v_mov_b32_dpp v200, v55 quad_perm:[1,0,3,2] row_mask:0xf bank_mask:0xf
	v_cndmask_b32_dpp v201, v51, v200, vcc quad_perm:[1,0,3,2] row_mask:0xf bank_mask:0xf
	v_cndmask_b32_e32 v55, v201, v55, vcc
	v_cndmask_b32_e32 v51, v51, v201, vcc
	v_mov_b32_dpp v200, v56 quad_perm:[1,0,3,2] row_mask:0xf bank_mask:0xf
	v_cndmask_b32_dpp v201, v52, v200, vcc quad_perm:[1,0,3,2] row_mask:0xf bank_mask:0xf
	v_cndmask_b32_e32 v56, v201, v56, vcc
	v_cndmask_b32_e32 v52, v52, v201, vcc
	v_mov_b32_dpp v200, v57 quad_perm:[1,0,3,2] row_mask:0xf bank_mask:0xf
	v_cndmask_b32_dpp v201, v53, v200, vcc quad_perm:[1,0,3,2] row_mask:0xf bank_mask:0xf
	v_cndmask_b32_e32 v57, v201, v57, vcc
	v_cndmask_b32_e32 v53, v53, v201, vcc
	v_mov_b32_dpp v200, v62 quad_perm:[1,0,3,2] row_mask:0xf bank_mask:0xf
	v_cndmask_b32_dpp v201, v58, v200, vcc quad_perm:[1,0,3,2] row_mask:0xf bank_mask:0xf
	v_cndmask_b32_e32 v62, v201, v62, vcc
	v_cndmask_b32_e32 v58, v58, v201, vcc
	v_mov_b32_dpp v200, v63 quad_perm:[1,0,3,2] row_mask:0xf bank_mask:0xf
	v_cndmask_b32_dpp v201, v59, v200, vcc quad_perm:[1,0,3,2] row_mask:0xf bank_mask:0xf
	v_cndmask_b32_e32 v63, v201, v63, vcc
	v_cndmask_b32_e32 v59, v59, v201, vcc
	v_mov_b32_dpp v200, v64 quad_perm:[1,0,3,2] row_mask:0xf bank_mask:0xf
	v_cndmask_b32_dpp v201, v60, v200, vcc quad_perm:[1,0,3,2] row_mask:0xf bank_mask:0xf
	v_cndmask_b32_e32 v64, v201, v64, vcc
	v_cndmask_b32_e32 v60, v60, v201, vcc
	v_mov_b32_dpp v200, v65 quad_perm:[1,0,3,2] row_mask:0xf bank_mask:0xf
	v_cndmask_b32_dpp v201, v61, v200, vcc quad_perm:[1,0,3,2] row_mask:0xf bank_mask:0xf
	v_cndmask_b32_e32 v65, v201, v65, vcc
	v_cndmask_b32_e32 v61, v61, v201, vcc
	s_waitcnt vmcnt(24)
;     ...
; #pragma unroll
;     for (int ai = 0; ai < 2; ++ai)
; #pragma unroll
;       for (int m = 0; m < 4; ++m)
;         epi(brow + ai * HALF + wr * 64 + m * 16 + fr, bcol + wc * 32, fq, acc[ai][0][m][0], acc[ai][0][m][1], acc[ai][1][m][0], acc[ai][1][m][1]);
	v_pk_add_f32 v[168:169], v[54:55], v[168:169]
	v_pk_add_f32 v[170:171], v[56:57], v[170:171]
	v_pk_add_f32 v[172:173], v[50:51], v[172:173]
	v_pk_add_f32 v[174:175], v[52:53], v[174:175]
	v_pk_add_f32 v[176:177], v[62:63], v[176:177]
	v_pk_add_f32 v[178:179], v[64:65], v[178:179]
	v_pk_add_f32 v[180:181], v[58:59], v[180:181]
	v_pk_add_f32 v[182:183], v[60:61], v[182:183]
	global_store_dwordx4 v[138:139], v[168:171], off sc1
	global_store_dwordx4 v[140:141], v[172:175], off sc1
	global_store_dwordx4 v[138:139], v[176:179], off offset:512 sc1
	global_store_dwordx4 v[140:141], v[180:183], off offset:512 sc1
	v_mov_b32_dpp v200, v38 quad_perm:[1,0,3,2] row_mask:0xf bank_mask:0xf
	v_cndmask_b32_dpp v201, v34, v200, vcc quad_perm:[1,0,3,2] row_mask:0xf bank_mask:0xf
	v_cndmask_b32_e32 v38, v201, v38, vcc
	v_cndmask_b32_e32 v34, v34, v201, vcc
	v_mov_b32_dpp v200, v39 quad_perm:[1,0,3,2] row_mask:0xf bank_mask:0xf
	v_cndmask_b32_dpp v201, v35, v200, vcc quad_perm:[1,0,3,2] row_mask:0xf bank_mask:0xf
	v_cndmask_b32_e32 v39, v201, v39, vcc
	v_cndmask_b32_e32 v35, v35, v201, vcc
	v_mov_b32_dpp v200, v40 quad_perm:[1,0,3,2] row_mask:0xf bank_mask:0xf
	v_cndmask_b32_dpp v201, v36, v200, vcc quad_perm:[1,0,3,2] row_mask:0xf bank_mask:0xf
	v_cndmask_b32_e32 v40, v201, v40, vcc
	v_cndmask_b32_e32 v36, v36, v201, vcc
	v_mov_b32_dpp v200, v41 quad_perm:[1,0,3,2] row_mask:0xf bank_mask:0xf
	v_cndmask_b32_dpp v201, v37, v200, vcc quad_perm:[1,0,3,2] row_mask:0xf bank_mask:0xf
	v_cndmask_b32_e32 v41, v201, v41, vcc
	v_cndmask_b32_e32 v37, v37, v201, vcc
	v_mov_b32_dpp v200, v46 quad_perm:[1,0,3,2] row_mask:0xf bank_mask:0xf
	v_cndmask_b32_dpp v201, v42, v200, vcc quad_perm:[1,0,3,2] row_mask:0xf bank_mask:0xf
	v_cndmask_b32_e32 v46, v201, v46, vcc
	v_cndmask_b32_e32 v42, v42, v201, vcc
	v_mov_b32_dpp v200, v47 quad_perm:[1,0,3,2] row_mask:0xf bank_mask:0xf
	v_cndmask_b32_dpp v201, v43, v200, vcc quad_perm:[1,0,3,2] row_mask:0xf bank_mask:0xf
	v_cndmask_b32_e32 v47, v201, v47, vcc
	v_cndmask_b32_e32 v43, v43, v201, vcc
	v_mov_b32_dpp v200, v48 quad_perm:[1,0,3,2] row_mask:0xf bank_mask:0xf
	v_cndmask_b32_dpp v201, v44, v200, vcc quad_perm:[1,0,3,2] row_mask:0xf bank_mask:0xf
	v_cndmask_b32_e32 v48, v201, v48, vcc
	v_cndmask_b32_e32 v44, v44, v201, vcc
	v_mov_b32_dpp v200, v49 quad_perm:[1,0,3,2] row_mask:0xf bank_mask:0xf
	v_cndmask_b32_dpp v201, v45, v200, vcc quad_perm:[1,0,3,2] row_mask:0xf bank_mask:0xf
	v_cndmask_b32_e32 v49, v201, v49, vcc
	v_cndmask_b32_e32 v45, v45, v201, vcc
	s_waitcnt vmcnt(20)
	v_pk_add_f32 v[184:185], v[38:39], v[184:185]
	v_pk_add_f32 v[186:187], v[40:41], v[186:187]
	v_pk_add_f32 v[188:189], v[34:35], v[188:189]
	v_pk_add_f32 v[190:191], v[36:37], v[190:191]
	v_pk_add_f32 v[192:193], v[46:47], v[192:193]
	v_pk_add_f32 v[194:195], v[48:49], v[194:195]
	v_pk_add_f32 v[196:197], v[42:43], v[196:197]
	v_pk_add_f32 v[198:199], v[44:45], v[198:199]
	global_store_dwordx4 v[142:143], v[184:187], off sc1
	global_store_dwordx4 v[144:145], v[188:191], off sc1
	global_store_dwordx4 v[142:143], v[192:195], off offset:512 sc1
	global_store_dwordx4 v[144:145], v[196:199], off offset:512 sc1
	v_mov_b32_dpp v200, v22 quad_perm:[1,0,3,2] row_mask:0xf bank_mask:0xf
	v_cndmask_b32_dpp v201, v18, v200, vcc quad_perm:[1,0,3,2] row_mask:0xf bank_mask:0xf
	v_cndmask_b32_e32 v22, v201, v22, vcc
	v_cndmask_b32_e32 v18, v18, v201, vcc
	v_mov_b32_dpp v200, v23 quad_perm:[1,0,3,2] row_mask:0xf bank_mask:0xf
	v_cndmask_b32_dpp v201, v19, v200, vcc quad_perm:[1,0,3,2] row_mask:0xf bank_mask:0xf
	v_cndmask_b32_e32 v23, v201, v23, vcc
	v_cndmask_b32_e32 v19, v19, v201, vcc
	v_mov_b32_dpp v200, v24 quad_perm:[1,0,3,2] row_mask:0xf bank_mask:0xf
	v_cndmask_b32_dpp v201, v20, v200, vcc quad_perm:[1,0,3,2] row_mask:0xf bank_mask:0xf
	v_cndmask_b32_e32 v24, v201, v24, vcc
	v_cndmask_b32_e32 v20, v20, v201, vcc
	v_mov_b32_dpp v200, v25 quad_perm:[1,0,3,2] row_mask:0xf bank_mask:0xf
	v_cndmask_b32_dpp v201, v21, v200, vcc quad_perm:[1,0,3,2] row_mask:0xf bank_mask:0xf
	v_cndmask_b32_e32 v25, v201, v25, vcc
	v_cndmask_b32_e32 v21, v21, v201, vcc
	v_mov_b32_dpp v200, v30 quad_perm:[1,0,3,2] row_mask:0xf bank_mask:0xf
	v_cndmask_b32_dpp v201, v26, v200, vcc quad_perm:[1,0,3,2] row_mask:0xf bank_mask:0xf
	v_cndmask_b32_e32 v30, v201, v30, vcc
	v_cndmask_b32_e32 v26, v26, v201, vcc
	v_mov_b32_dpp v200, v31 quad_perm:[1,0,3,2] row_mask:0xf bank_mask:0xf
	v_cndmask_b32_dpp v201, v27, v200, vcc quad_perm:[1,0,3,2] row_mask:0xf bank_mask:0xf
	v_cndmask_b32_e32 v31, v201, v31, vcc
	v_cndmask_b32_e32 v27, v27, v201, vcc
	v_mov_b32_dpp v200, v32 quad_perm:[1,0,3,2] row_mask:0xf bank_mask:0xf
	v_cndmask_b32_dpp v201, v28, v200, vcc quad_perm:[1,0,3,2] row_mask:0xf bank_mask:0xf
	v_cndmask_b32_e32 v32, v201, v32, vcc
	v_cndmask_b32_e32 v28, v28, v201, vcc
	v_mov_b32_dpp v200, v33 quad_perm:[1,0,3,2] row_mask:0xf bank_mask:0xf
	v_cndmask_b32_dpp v201, v29, v200, vcc quad_perm:[1,0,3,2] row_mask:0xf bank_mask:0xf
	v_cndmask_b32_e32 v33, v201, v33, vcc
	v_cndmask_b32_e32 v29, v29, v201, vcc
	s_waitcnt vmcnt(16)
; #define WAIT_V(n) asm volatile("s_waitcnt vmcnt(" #n ")" ::: "memory")
;     ...
;   if (!have_next) { WAIT_V(0); __syncthreads(); }
	v_pk_add_f32 v[220:221], v[22:23], v[220:221]
	v_pk_add_f32 v[222:223], v[24:25], v[222:223]
	v_pk_add_f32 v[224:225], v[18:19], v[224:225]
	v_pk_add_f32 v[226:227], v[20:21], v[226:227]
	v_pk_add_f32 v[228:229], v[30:31], v[228:229]
	v_pk_add_f32 v[230:231], v[32:33], v[230:231]
	v_pk_add_f32 v[232:233], v[26:27], v[232:233]
	v_pk_add_f32 v[234:235], v[28:29], v[234:235]
	global_store_dwordx4 v[146:147], v[220:223], off sc1
	global_store_dwordx4 v[148:149], v[224:227], off sc1
	global_store_dwordx4 v[146:147], v[228:231], off offset:512 sc1
	global_store_dwordx4 v[148:149], v[232:235], off offset:512 sc1
	v_mov_b32_dpp v200, v14 quad_perm:[1,0,3,2] row_mask:0xf bank_mask:0xf
	v_cndmask_b32_dpp v201, v6, v200, vcc quad_perm:[1,0,3,2] row_mask:0xf bank_mask:0xf
	v_cndmask_b32_e32 v14, v201, v14, vcc
	v_cndmask_b32_e32 v6, v6, v201, vcc
	v_mov_b32_dpp v200, v15 quad_perm:[1,0,3,2] row_mask:0xf bank_mask:0xf
	v_cndmask_b32_dpp v201, v7, v200, vcc quad_perm:[1,0,3,2] row_mask:0xf bank_mask:0xf
	v_cndmask_b32_e32 v15, v201, v15, vcc
	v_cndmask_b32_e32 v7, v7, v201, vcc
	v_mov_b32_dpp v200, v16 quad_perm:[1,0,3,2] row_mask:0xf bank_mask:0xf
	v_cndmask_b32_dpp v201, v8, v200, vcc quad_perm:[1,0,3,2] row_mask:0xf bank_mask:0xf
	v_cndmask_b32_e32 v16, v201, v16, vcc
	v_cndmask_b32_e32 v8, v8, v201, vcc
	v_mov_b32_dpp v200, v17 quad_perm:[1,0,3,2] row_mask:0xf bank_mask:0xf
	v_cndmask_b32_dpp v201, v9, v200, vcc quad_perm:[1,0,3,2] row_mask:0xf bank_mask:0xf
	v_cndmask_b32_e32 v17, v201, v17, vcc
	v_cndmask_b32_e32 v9, v9, v201, vcc
	v_mov_b32_dpp v200, v10 quad_perm:[1,0,3,2] row_mask:0xf bank_mask:0xf
	v_cndmask_b32_dpp v201, v2, v200, vcc quad_perm:[1,0,3,2] row_mask:0xf bank_mask:0xf
	v_cndmask_b32_e32 v10, v201, v10, vcc
	v_cndmask_b32_e32 v2, v2, v201, vcc
	v_mov_b32_dpp v200, v11 quad_perm:[1,0,3,2] row_mask:0xf bank_mask:0xf
	v_cndmask_b32_dpp v201, v3, v200, vcc quad_perm:[1,0,3,2] row_mask:0xf bank_mask:0xf
	v_cndmask_b32_e32 v11, v201, v11, vcc
	v_cndmask_b32_e32 v3, v3, v201, vcc
	v_mov_b32_dpp v200, v12 quad_perm:[1,0,3,2] row_mask:0xf bank_mask:0xf
	v_cndmask_b32_dpp v201, v4, v200, vcc quad_perm:[1,0,3,2] row_mask:0xf bank_mask:0xf
	v_cndmask_b32_e32 v12, v201, v12, vcc
	v_cndmask_b32_e32 v4, v4, v201, vcc
	v_mov_b32_dpp v200, v13 quad_perm:[1,0,3,2] row_mask:0xf bank_mask:0xf
	v_cndmask_b32_dpp v201, v5, v200, vcc quad_perm:[1,0,3,2] row_mask:0xf bank_mask:0xf
	v_cndmask_b32_e32 v13, v201, v13, vcc
	v_cndmask_b32_e32 v5, v5, v201, vcc
	s_waitcnt vmcnt(12)
	v_pk_add_f32 v[236:237], v[14:15], v[236:237]
	v_pk_add_f32 v[238:239], v[16:17], v[238:239]
	v_pk_add_f32 v[240:241], v[6:7], v[240:241]
	v_pk_add_f32 v[242:243], v[8:9], v[242:243]
	v_pk_add_f32 v[244:245], v[10:11], v[244:245]
	v_pk_add_f32 v[246:247], v[12:13], v[246:247]
	v_pk_add_f32 v[248:249], v[2:3], v[248:249]
	v_pk_add_f32 v[250:251], v[4:5], v[250:251]
	global_store_dwordx4 v[150:151], v[236:239], off sc1
	global_store_dwordx4 v[152:153], v[240:243], off sc1
	global_store_dwordx4 v[150:151], v[244:247], off offset:512 sc1
	global_store_dwordx4 v[152:153], v[248:251], off offset:512 sc1
	v_cmp_ne_u32_e64 s[4:5], 1, v0
	s_andn2_b64 vcc, exec, s[2:3]
	s_cbranch_vccnz .LBB0_1551
	s_waitcnt vmcnt(0)
	s_waitcnt lgkmcnt(0)
	s_barrier
	s_branch .LBB0_1551
